# on top of v191: nt hints on the read-once tile loads (LDS-DMA) of the prompt-retention output phase and on ROW3's last read of the residual stream
# speedup vs baseline: 1.0096x; 1.0096x over previous
.LR3_unit:
	s_and_b32 s80, s64, 31
	s_lshr_b32 s81, s64, 5
	s_and_b32 s66, s81, 7
	s_lshr_b32 s81, s81, 3
	s_lshl_b32 s81, s81, 12
	s_lshl_b32 s80, s80, 7
	s_add_u32 s80, s80, s81
	s_mul_i32 s82, s80, 0x5c00
	s_lshl_b32 s83, s66, 8
	s_add_u32 s82, s82, s83
	s_add_u32 s82, s82, 0xc00
	s_add_u32 s68, s52, s82
	s_addc_u32 s69, s53, 0
	s_add_u32 s84, s83, 0x2000
	s_add_u32 s72, s68, s84
	s_addc_u32 s73, s69, 0
	s_lshl_b32 s84, s80, 12
	s_lshl_b32 s85, s66, 9
	s_add_u32 s84, s84, s85
	s_add_u32 s74, s58, s84
	s_addc_u32 s75, s59, 0
	s_mul_i32 s84, s65, 0x17000
	s_add_u32 s84, s84, 0x800
	s_add_u32 s86, s68, s84
	s_addc_u32 s87, s69, 0
	s_add_u32 s88, s67, 0x10000
	s_mov_b32 m0, s88
	v_lshl_add_u64 v[4:5], s[86:87], 0, v[138:139]
	global_load_lds_dwordx4 v[4:5], off nt
	s_add_u32 s86, s86, 0xb8000
	s_addc_u32 s87, s87, 0
	s_add_u32 s88, s88, 0x2000
	s_mov_b32 m0, s88
	v_lshl_add_u64 v[4:5], s[86:87], 0, v[138:139]
	global_load_lds_dwordx4 v[4:5], off nt
	s_add_u32 s86, s86, 0xb8000
	s_addc_u32 s87, s87, 0
	s_add_u32 s88, s88, 0x2000
	s_mov_b32 m0, s88
	v_lshl_add_u64 v[4:5], s[86:87], 0, v[138:139]
	global_load_lds_dwordx4 v[4:5], off nt
	s_add_u32 s86, s86, 0xb8000
	s_addc_u32 s87, s87, 0
	s_add_u32 s88, s88, 0x2000
	s_mov_b32 m0, s88
	v_lshl_add_u64 v[4:5], s[86:87], 0, v[138:139]
	global_load_lds_dwordx4 v[4:5], off nt
	global_load_dwordx4 v[20:23], v9, s[68:69] offset:0
	global_load_dwordx4 v[24:27], v9, s[68:69] offset:64
	global_load_dwordx4 v[28:31], v9, s[68:69] offset:128
	global_load_dwordx4 v[32:35], v9, s[68:69] offset:192
	s_lshl_b32 s84, s64, 16
	s_add_u32 s84, s84, s67
	s_add_u32 s76, s54, s84
	s_addc_u32 s77, s55, 0
	s_add_u32 s78, s56, s84
	s_addc_u32 s79, s57, 0
	s_mov_b32 s88, s67
	s_mov_b32 m0, s88
	v_lshl_add_u64 v[4:5], s[76:77], 0, v[18:19]
	global_load_lds_dwordx4 v[4:5], off nt
	s_add_u32 s76, s76, 0x2000
	s_addc_u32 s77, s77, 0
	s_add_u32 s88, s88, 0x2000
	s_mov_b32 m0, s88
	v_lshl_add_u64 v[4:5], s[76:77], 0, v[18:19]
	global_load_lds_dwordx4 v[4:5], off nt
	s_add_u32 s76, s76, 0x2000
	s_addc_u32 s77, s77, 0
	s_add_u32 s88, s88, 0x2000
	s_mov_b32 m0, s88
	v_lshl_add_u64 v[4:5], s[76:77], 0, v[18:19]
	global_load_lds_dwordx4 v[4:5], off nt
	s_add_u32 s76, s76, 0x2000
	s_addc_u32 s77, s77, 0
	s_add_u32 s88, s88, 0x2000
	s_mov_b32 m0, s88
	v_lshl_add_u64 v[4:5], s[76:77], 0, v[18:19]
	global_load_lds_dwordx4 v[4:5], off nt
	s_add_u32 s76, s76, 0x2000
	s_addc_u32 s77, s77, 0
	s_add_u32 s88, s88, 0x2000
	s_mov_b32 m0, s88
	v_lshl_add_u64 v[4:5], s[76:77], 0, v[18:19]
	global_load_lds_dwordx4 v[4:5], off nt
	s_add_u32 s76, s76, 0x2000
	s_addc_u32 s77, s77, 0
	s_add_u32 s88, s88, 0x2000
	s_mov_b32 m0, s88
	v_lshl_add_u64 v[4:5], s[76:77], 0, v[18:19]
	global_load_lds_dwordx4 v[4:5], off nt
	s_add_u32 s76, s76, 0x2000
	s_addc_u32 s77, s77, 0
	s_add_u32 s88, s88, 0x2000
	s_mov_b32 m0, s88
	v_lshl_add_u64 v[4:5], s[76:77], 0, v[18:19]
	global_load_lds_dwordx4 v[4:5], off nt
	s_add_u32 s76, s76, 0x2000
	s_addc_u32 s77, s77, 0
	s_add_u32 s88, s88, 0x2000
	s_mov_b32 m0, s88
	v_lshl_add_u64 v[4:5], s[76:77], 0, v[18:19]
	global_load_lds_dwordx4 v[4:5], off nt
	s_sub_i32 s85, -5, s66
	v_cvt_f32_i32_e32 v4, s85
	v_exp_f32_e32 v4, v4
	s_nop 0
	v_sub_f32_e32 v4, 1.0, v4
	v_log_f32_e32 v16, v4
	s_nop 0
	v_mul_f32_e32 v126, v129, v16
	v_exp_f32_e32 v126, v126
	s_waitcnt vmcnt(8)
	s_barrier
	ds_read_b128 v[52:55], v146 offset:0
	ds_read_b128 v[56:59], v147 offset:0
	ds_read_b128 v[60:63], v148 offset:0
	ds_read_b128 v[64:67], v149 offset:0
	ds_read_b128 v[68:71], v146 offset:4096
	ds_read_b128 v[72:75], v147 offset:4096
	ds_read_b128 v[76:79], v148 offset:4096
	ds_read_b128 v[80:83], v149 offset:4096
	ds_read_b128 v[84:87], v146 offset:8192
	ds_read_b128 v[88:91], v147 offset:8192
	ds_read_b128 v[92:95], v148 offset:8192
	ds_read_b128 v[96:99], v149 offset:8192
	ds_read_b128 v[100:103], v146 offset:12288
	ds_read_b128 v[104:107], v147 offset:12288
	ds_read_b128 v[108:111], v148 offset:12288
	ds_read_b128 v[112:115], v149 offset:12288
	ds_read_b128 v[158:161], v146 offset:16384
	ds_read_b128 v[162:165], v147 offset:16384
	ds_read_b128 v[166:169], v148 offset:16384
	ds_read_b128 v[170:173], v149 offset:16384
	ds_read_b128 v[174:177], v146 offset:20480
	ds_read_b128 v[178:181], v147 offset:20480
	ds_read_b128 v[182:185], v148 offset:20480
	ds_read_b128 v[186:189], v149 offset:20480
	ds_read_b128 v[190:193], v146 offset:24576
	ds_read_b128 v[194:197], v147 offset:24576
	ds_read_b128 v[198:201], v148 offset:24576
	ds_read_b128 v[202:205], v149 offset:24576
	ds_read_b128 v[206:209], v146 offset:28672
	ds_read_b128 v[210:213], v147 offset:28672
	ds_read_b128 v[214:217], v148 offset:28672
	ds_read_b128 v[218:221], v149 offset:28672
	s_waitcnt lgkmcnt(0)
	s_barrier
	s_add_u32 s88, s67, 0x10000
	s_mov_b32 m0, s88
	v_lshl_add_u64 v[4:5], s[78:79], 0, v[18:19]
	global_load_lds_dwordx4 v[4:5], off nt
	s_add_u32 s78, s78, 0x2000
	s_addc_u32 s79, s79, 0
	s_add_u32 s88, s88, 0x2000
	s_mov_b32 m0, s88
	v_lshl_add_u64 v[4:5], s[78:79], 0, v[18:19]
	global_load_lds_dwordx4 v[4:5], off nt
	s_add_u32 s78, s78, 0x2000
	s_addc_u32 s79, s79, 0
	s_add_u32 s88, s88, 0x2000
	s_mov_b32 m0, s88
	v_lshl_add_u64 v[4:5], s[78:79], 0, v[18:19]
	global_load_lds_dwordx4 v[4:5], off nt
	s_add_u32 s78, s78, 0x2000
	s_addc_u32 s79, s79, 0
	s_add_u32 s88, s88, 0x2000
	s_mov_b32 m0, s88
	v_lshl_add_u64 v[4:5], s[78:79], 0, v[18:19]
	global_load_lds_dwordx4 v[4:5], off nt
	s_add_u32 s78, s78, 0x2000
	s_addc_u32 s79, s79, 0
	s_add_u32 s88, s88, 0x2000
	s_mov_b32 m0, s88
	v_lshl_add_u64 v[4:5], s[78:79], 0, v[18:19]
	global_load_lds_dwordx4 v[4:5], off nt
	s_add_u32 s78, s78, 0x2000
	s_addc_u32 s79, s79, 0
	s_add_u32 s88, s88, 0x2000
	s_mov_b32 m0, s88
	v_lshl_add_u64 v[4:5], s[78:79], 0, v[18:19]
	global_load_lds_dwordx4 v[4:5], off nt
	s_add_u32 s78, s78, 0x2000
	s_addc_u32 s79, s79, 0
	s_add_u32 s88, s88, 0x2000
	s_mov_b32 m0, s88
	v_lshl_add_u64 v[4:5], s[78:79], 0, v[18:19]
	global_load_lds_dwordx4 v[4:5], off nt
	s_add_u32 s78, s78, 0x2000
	s_addc_u32 s79, s79, 0
	s_add_u32 s88, s88, 0x2000
	s_mov_b32 m0, s88
	v_lshl_add_u64 v[4:5], s[78:79], 0, v[18:19]
	global_load_lds_dwordx4 v[4:5], off nt
	v_mfma_f32_16x16x32_bf16 v[222:225], v[52:55], v[20:23], 0
	v_mfma_f32_16x16x32_bf16 v[222:225], v[56:59], v[24:27], v[222:225]
	v_mfma_f32_16x16x32_bf16 v[222:225], v[60:63], v[28:31], v[222:225]
	v_mfma_f32_16x16x32_bf16 v[222:225], v[64:67], v[32:35], v[222:225]
	v_mfma_f32_16x16x32_bf16 v[226:229], v[68:71], v[20:23], 0
	v_mfma_f32_16x16x32_bf16 v[226:229], v[72:75], v[24:27], v[226:229]
	v_mfma_f32_16x16x32_bf16 v[226:229], v[76:79], v[28:31], v[226:229]
	v_mfma_f32_16x16x32_bf16 v[226:229], v[80:83], v[32:35], v[226:229]
	v_mfma_f32_16x16x32_bf16 v[230:233], v[84:87], v[20:23], 0
	v_mfma_f32_16x16x32_bf16 v[230:233], v[88:91], v[24:27], v[230:233]
	v_mfma_f32_16x16x32_bf16 v[230:233], v[92:95], v[28:31], v[230:233]
	v_mfma_f32_16x16x32_bf16 v[230:233], v[96:99], v[32:35], v[230:233]
	v_mfma_f32_16x16x32_bf16 v[236:239], v[100:103], v[20:23], 0
	v_mfma_f32_16x16x32_bf16 v[236:239], v[104:107], v[24:27], v[236:239]
	v_mfma_f32_16x16x32_bf16 v[236:239], v[108:111], v[28:31], v[236:239]
	v_mfma_f32_16x16x32_bf16 v[236:239], v[112:115], v[32:35], v[236:239]
	v_mfma_f32_16x16x32_bf16 v[240:243], v[158:161], v[20:23], 0
	v_mfma_f32_16x16x32_bf16 v[240:243], v[162:165], v[24:27], v[240:243]
	v_mfma_f32_16x16x32_bf16 v[240:243], v[166:169], v[28:31], v[240:243]
	v_mfma_f32_16x16x32_bf16 v[240:243], v[170:173], v[32:35], v[240:243]
	v_mfma_f32_16x16x32_bf16 v[244:247], v[174:177], v[20:23], 0
	v_mfma_f32_16x16x32_bf16 v[244:247], v[178:181], v[24:27], v[244:247]
	v_mfma_f32_16x16x32_bf16 v[244:247], v[182:185], v[28:31], v[244:247]
	v_mfma_f32_16x16x32_bf16 v[244:247], v[186:189], v[32:35], v[244:247]
	v_mfma_f32_16x16x32_bf16 v[248:251], v[190:193], v[20:23], 0
	v_mfma_f32_16x16x32_bf16 v[248:251], v[194:197], v[24:27], v[248:251]
	v_mfma_f32_16x16x32_bf16 v[248:251], v[198:201], v[28:31], v[248:251]
	v_mfma_f32_16x16x32_bf16 v[248:251], v[202:205], v[32:35], v[248:251]
	v_mfma_f32_16x16x32_bf16 v[252:255], v[206:209], v[20:23], 0
	v_mfma_f32_16x16x32_bf16 v[252:255], v[210:213], v[24:27], v[252:255]
	v_mfma_f32_16x16x32_bf16 v[252:255], v[214:217], v[28:31], v[252:255]
	v_mfma_f32_16x16x32_bf16 v[252:255], v[218:221], v[32:35], v[252:255]
	v_add_f32_e32 v4, 0x00000000, v125
	v_mul_f32_e32 v4, v4, v16
	v_exp_f32_e32 v4, v4
	s_nop 4
	v_cmp_le_f32_e32 vcc, 0x00000000, v125
	v_add_f32_e32 v5, 0xbf800000, v125
	v_mul_f32_e32 v5, v5, v16
	v_cndmask_b32_e32 v222, 0, v222, vcc
	v_exp_f32_e32 v5, v5
	v_mul_f32_e32 v222, v222, v4
	v_cmp_le_f32_e32 vcc, 0x3f800000, v125
	v_add_f32_e32 v4, 0xc0000000, v125
	v_mul_f32_e32 v4, v4, v16
	v_cndmask_b32_e32 v223, 0, v223, vcc
	v_exp_f32_e32 v4, v4
	v_mul_f32_e32 v223, v223, v5
	v_cmp_le_f32_e32 vcc, 0x40000000, v125
	v_add_f32_e32 v5, 0xc0400000, v125
	v_mul_f32_e32 v5, v5, v16
	v_cndmask_b32_e32 v224, 0, v224, vcc
	v_exp_f32_e32 v5, v5
	v_mul_f32_e32 v224, v224, v4
	v_cmp_le_f32_e32 vcc, 0x40400000, v125
	v_add_f32_e32 v4, 0xc1800000, v125
	v_mul_f32_e32 v4, v4, v16
	v_cndmask_b32_e32 v225, 0, v225, vcc
	v_exp_f32_e32 v4, v4
	v_mul_f32_e32 v225, v225, v5
	v_cmp_le_f32_e32 vcc, 0x41800000, v125
	v_add_f32_e32 v5, 0xc1880000, v125
	v_mul_f32_e32 v5, v5, v16
	v_cndmask_b32_e32 v226, 0, v226, vcc
	v_exp_f32_e32 v5, v5
	v_mul_f32_e32 v226, v226, v4
	v_cmp_le_f32_e32 vcc, 0x41880000, v125
	v_add_f32_e32 v4, 0xc1900000, v125
	v_mul_f32_e32 v4, v4, v16
	v_cndmask_b32_e32 v227, 0, v227, vcc
	v_exp_f32_e32 v4, v4
	v_mul_f32_e32 v227, v227, v5
	v_cmp_le_f32_e32 vcc, 0x41900000, v125
	v_add_f32_e32 v5, 0xc1980000, v125
	v_mul_f32_e32 v5, v5, v16
	v_cndmask_b32_e32 v228, 0, v228, vcc
	v_exp_f32_e32 v5, v5
	v_mul_f32_e32 v228, v228, v4
	v_cmp_le_f32_e32 vcc, 0x41980000, v125
	v_add_f32_e32 v4, 0xc2000000, v125
	v_mul_f32_e32 v4, v4, v16
	v_cndmask_b32_e32 v229, 0, v229, vcc
	v_exp_f32_e32 v4, v4
	v_mul_f32_e32 v229, v229, v5
	v_cmp_le_f32_e32 vcc, 0x42000000, v125
	v_add_f32_e32 v5, 0xc2040000, v125
	v_mul_f32_e32 v5, v5, v16
	v_cndmask_b32_e32 v230, 0, v230, vcc
	v_exp_f32_e32 v5, v5
	v_mul_f32_e32 v230, v230, v4
	v_cmp_le_f32_e32 vcc, 0x42040000, v125
	v_add_f32_e32 v4, 0xc2080000, v125
	v_mul_f32_e32 v4, v4, v16
	v_cndmask_b32_e32 v231, 0, v231, vcc
	v_exp_f32_e32 v4, v4
	v_mul_f32_e32 v231, v231, v5
	v_cmp_le_f32_e32 vcc, 0x42080000, v125
	v_add_f32_e32 v5, 0xc20c0000, v125
	v_mul_f32_e32 v5, v5, v16
	v_cndmask_b32_e32 v232, 0, v232, vcc
	v_exp_f32_e32 v5, v5
	v_mul_f32_e32 v232, v232, v4
	v_cmp_le_f32_e32 vcc, 0x420c0000, v125
	v_add_f32_e32 v4, 0xc2400000, v125
	v_mul_f32_e32 v4, v4, v16
	v_cndmask_b32_e32 v233, 0, v233, vcc
	v_exp_f32_e32 v4, v4
	v_mul_f32_e32 v233, v233, v5
	v_cmp_le_f32_e32 vcc, 0x42400000, v125
	v_add_f32_e32 v5, 0xc2440000, v125
	v_mul_f32_e32 v5, v5, v16
	v_cndmask_b32_e32 v236, 0, v236, vcc
	v_exp_f32_e32 v5, v5
	v_mul_f32_e32 v236, v236, v4
	v_cmp_le_f32_e32 vcc, 0x42440000, v125
	v_add_f32_e32 v4, 0xc2480000, v125
	v_mul_f32_e32 v4, v4, v16
	v_cndmask_b32_e32 v237, 0, v237, vcc
	v_exp_f32_e32 v4, v4
	v_mul_f32_e32 v237, v237, v5
	v_cmp_le_f32_e32 vcc, 0x42480000, v125
	v_add_f32_e32 v5, 0xc24c0000, v125
	v_mul_f32_e32 v5, v5, v16
	v_cndmask_b32_e32 v238, 0, v238, vcc
	v_exp_f32_e32 v5, v5
	v_mul_f32_e32 v238, v238, v4
	v_cmp_le_f32_e32 vcc, 0x424c0000, v125
	v_add_f32_e32 v4, 0xc2800000, v125
	v_mul_f32_e32 v4, v4, v16
	v_cndmask_b32_e32 v239, 0, v239, vcc
	v_exp_f32_e32 v4, v4
	v_mul_f32_e32 v239, v239, v5
	v_cmp_le_f32_e32 vcc, 0x42800000, v125
	v_add_f32_e32 v5, 0xc2820000, v125
	v_mul_f32_e32 v5, v5, v16
	v_cndmask_b32_e32 v240, 0, v240, vcc
	v_exp_f32_e32 v5, v5
	v_mul_f32_e32 v240, v240, v4
	v_cmp_le_f32_e32 vcc, 0x42820000, v125
	v_add_f32_e32 v4, 0xc2840000, v125
	v_mul_f32_e32 v4, v4, v16
	v_cndmask_b32_e32 v241, 0, v241, vcc
	v_exp_f32_e32 v4, v4
	v_mul_f32_e32 v241, v241, v5
	v_cmp_le_f32_e32 vcc, 0x42840000, v125
	v_add_f32_e32 v5, 0xc2860000, v125
	v_mul_f32_e32 v5, v5, v16
	v_cndmask_b32_e32 v242, 0, v242, vcc
	v_exp_f32_e32 v5, v5
	v_mul_f32_e32 v242, v242, v4
	v_cmp_le_f32_e32 vcc, 0x42860000, v125
	v_add_f32_e32 v4, 0xc2a00000, v125
	v_mul_f32_e32 v4, v4, v16
	v_cndmask_b32_e32 v243, 0, v243, vcc
	v_exp_f32_e32 v4, v4
	v_mul_f32_e32 v243, v243, v5
	v_cmp_le_f32_e32 vcc, 0x42a00000, v125
	v_add_f32_e32 v5, 0xc2a20000, v125
	v_mul_f32_e32 v5, v5, v16
	v_cndmask_b32_e32 v244, 0, v244, vcc
	v_exp_f32_e32 v5, v5
	v_mul_f32_e32 v244, v244, v4
	v_cmp_le_f32_e32 vcc, 0x42a20000, v125
	v_add_f32_e32 v4, 0xc2a40000, v125
	v_mul_f32_e32 v4, v4, v16
	v_cndmask_b32_e32 v245, 0, v245, vcc
	v_exp_f32_e32 v4, v4
	v_mul_f32_e32 v245, v245, v5
	v_cmp_le_f32_e32 vcc, 0x42a40000, v125
	v_add_f32_e32 v5, 0xc2a60000, v125
	v_mul_f32_e32 v5, v5, v16
	v_cndmask_b32_e32 v246, 0, v246, vcc
	v_exp_f32_e32 v5, v5
	v_mul_f32_e32 v246, v246, v4
	v_cmp_le_f32_e32 vcc, 0x42a60000, v125
	v_add_f32_e32 v4, 0xc2c00000, v125
	v_mul_f32_e32 v4, v4, v16
	v_cndmask_b32_e32 v247, 0, v247, vcc
	v_exp_f32_e32 v4, v4
	v_mul_f32_e32 v247, v247, v5
	v_cmp_le_f32_e32 vcc, 0x42c00000, v125
	v_add_f32_e32 v5, 0xc2c20000, v125
	v_mul_f32_e32 v5, v5, v16
	v_cndmask_b32_e32 v248, 0, v248, vcc
	v_exp_f32_e32 v5, v5
	v_mul_f32_e32 v248, v248, v4
	v_cmp_le_f32_e32 vcc, 0x42c20000, v125
	v_add_f32_e32 v4, 0xc2c40000, v125
	v_mul_f32_e32 v4, v4, v16
	v_cndmask_b32_e32 v249, 0, v249, vcc
	v_exp_f32_e32 v4, v4
	v_mul_f32_e32 v249, v249, v5
	v_cmp_le_f32_e32 vcc, 0x42c40000, v125
	v_add_f32_e32 v5, 0xc2c60000, v125
	v_mul_f32_e32 v5, v5, v16
	v_cndmask_b32_e32 v250, 0, v250, vcc
	v_exp_f32_e32 v5, v5
	v_mul_f32_e32 v250, v250, v4
	v_cmp_le_f32_e32 vcc, 0x42c60000, v125
	v_add_f32_e32 v4, 0xc2e00000, v125
	v_mul_f32_e32 v4, v4, v16
	v_cndmask_b32_e32 v251, 0, v251, vcc
	v_exp_f32_e32 v4, v4
	v_mul_f32_e32 v251, v251, v5
	v_cmp_le_f32_e32 vcc, 0x42e00000, v125
	v_add_f32_e32 v5, 0xc2e20000, v125
	v_mul_f32_e32 v5, v5, v16
	v_cndmask_b32_e32 v252, 0, v252, vcc
	v_exp_f32_e32 v5, v5
	v_mul_f32_e32 v252, v252, v4
	v_cmp_le_f32_e32 vcc, 0x42e20000, v125
	v_add_f32_e32 v4, 0xc2e40000, v125
	v_mul_f32_e32 v4, v4, v16
	v_cndmask_b32_e32 v253, 0, v253, vcc
	v_exp_f32_e32 v4, v4
	v_mul_f32_e32 v253, v253, v5
	v_cmp_le_f32_e32 vcc, 0x42e40000, v125
	v_add_f32_e32 v5, 0xc2e60000, v125
	v_mul_f32_e32 v5, v5, v16
	v_cndmask_b32_e32 v254, 0, v254, vcc
	v_exp_f32_e32 v5, v5
	v_mul_f32_e32 v254, v254, v4
	v_cmp_le_f32_e32 vcc, 0x42e60000, v125
	s_nop 1
	v_cndmask_b32_e32 v255, 0, v255, vcc
	v_mul_f32_e32 v255, v255, v5
	v_cvt_pk_bf16_f32 v36, v222, v223
	v_cvt_pk_bf16_f32 v37, v224, v225
	v_cvt_pk_bf16_f32 v38, v226, v227
	v_cvt_pk_bf16_f32 v39, v228, v229
	v_cvt_pk_bf16_f32 v40, v230, v231
	v_cvt_pk_bf16_f32 v41, v232, v233
	v_cvt_pk_bf16_f32 v42, v236, v237
	v_cvt_pk_bf16_f32 v43, v238, v239
	v_cvt_pk_bf16_f32 v44, v240, v241
	v_cvt_pk_bf16_f32 v45, v242, v243
	v_cvt_pk_bf16_f32 v46, v244, v245
	v_cvt_pk_bf16_f32 v47, v246, v247
	v_cvt_pk_bf16_f32 v48, v248, v249
	v_cvt_pk_bf16_f32 v49, v250, v251
	v_cvt_pk_bf16_f32 v50, v252, v253
	v_cvt_pk_bf16_f32 v51, v254, v255
	global_load_dwordx2 v[222:223], v140, s[72:73] offset:0
	global_load_dwordx2 v[224:225], v140, s[72:73] offset:32
	global_load_dwordx2 v[226:227], v140, s[72:73] offset:64
	global_load_dwordx2 v[228:229], v140, s[72:73] offset:96
	global_load_dwordx2 v[230:231], v140, s[72:73] offset:128
	global_load_dwordx2 v[232:233], v140, s[72:73] offset:160
	global_load_dwordx2 v[236:237], v140, s[72:73] offset:192
	global_load_dwordx2 v[238:239], v140, s[72:73] offset:224
	global_load_dwordx2 v[240:241], v140, s[72:73] offset:256
	global_load_dwordx2 v[242:243], v140, s[72:73] offset:288
	global_load_dwordx2 v[244:245], v140, s[72:73] offset:320
	global_load_dwordx2 v[246:247], v140, s[72:73] offset:352
	global_load_dwordx2 v[248:249], v140, s[72:73] offset:384
	global_load_dwordx2 v[250:251], v140, s[72:73] offset:416
	global_load_dwordx2 v[252:253], v140, s[72:73] offset:448
	global_load_dwordx2 v[254:255], v140, s[72:73] offset:480
	s_waitcnt vmcnt(16)
	s_barrier
	ds_read_b128 v[158:161], v142 offset:0
	ds_read_b128 v[162:165], v143 offset:0
	ds_read_b128 v[166:169], v144 offset:0
	ds_read_b128 v[170:173], v145 offset:0
	ds_read_b64 v[174:175], v150 offset:0
	ds_read_b64 v[176:177], v154 offset:0
	ds_read_b64 v[178:179], v151 offset:0
	ds_read_b64 v[180:181], v155 offset:0
	ds_read_b64 v[182:183], v152 offset:0
	ds_read_b64 v[184:185], v156 offset:0
	ds_read_b64 v[186:187], v153 offset:0
	ds_read_b64 v[188:189], v157 offset:0
	ds_read_b128 v[190:193], v142 offset:4096
	ds_read_b128 v[194:197], v143 offset:4096
	ds_read_b128 v[198:201], v144 offset:4096
	ds_read_b128 v[202:205], v145 offset:4096
	ds_read_b64 v[206:207], v150 offset:4096
	ds_read_b64 v[208:209], v154 offset:4096
	ds_read_b64 v[210:211], v151 offset:4096
	ds_read_b64 v[212:213], v155 offset:4096
	ds_read_b64 v[214:215], v152 offset:4096
	ds_read_b64 v[216:217], v156 offset:4096
	ds_read_b64 v[218:219], v153 offset:4096
	ds_read_b64 v[220:221], v157 offset:4096
	s_waitcnt lgkmcnt(12)
	v_mfma_f32_16x16x32_bf16 v[116:119], v[158:161], v[20:23], 0
	v_mfma_f32_16x16x32_bf16 v[116:119], v[162:165], v[24:27], v[116:119]
	v_mfma_f32_16x16x32_bf16 v[116:119], v[166:169], v[28:31], v[116:119]
	v_mfma_f32_16x16x32_bf16 v[116:119], v[170:173], v[32:35], v[116:119]
	v_mfma_f32_16x16x32_bf16 v[120:123], v[174:177], v[36:39], 0
	v_mfma_f32_16x16x32_bf16 v[120:123], v[178:181], v[40:43], v[120:123]
	v_mfma_f32_16x16x32_bf16 v[120:123], v[182:185], v[44:47], v[120:123]
	v_mfma_f32_16x16x32_bf16 v[120:123], v[186:189], v[48:51], v[120:123]
	ds_read_b128 v[158:161], v142 offset:8192
	ds_read_b128 v[162:165], v143 offset:8192
	ds_read_b128 v[166:169], v144 offset:8192
	ds_read_b128 v[170:173], v145 offset:8192
	ds_read_b64 v[174:175], v150 offset:8192
	ds_read_b64 v[176:177], v154 offset:8192
	ds_read_b64 v[178:179], v151 offset:8192
	ds_read_b64 v[180:181], v155 offset:8192
	ds_read_b64 v[182:183], v152 offset:8192
	ds_read_b64 v[184:185], v156 offset:8192
	ds_read_b64 v[186:187], v153 offset:8192
	ds_read_b64 v[188:189], v157 offset:8192
	s_waitcnt lgkmcnt(12)
	v_mfma_f32_16x16x32_bf16 v[130:133], v[190:193], v[20:23], 0
	v_mfma_f32_16x16x32_bf16 v[130:133], v[194:197], v[24:27], v[130:133]
	v_mfma_f32_16x16x32_bf16 v[130:133], v[198:201], v[28:31], v[130:133]
	v_mfma_f32_16x16x32_bf16 v[130:133], v[202:205], v[32:35], v[130:133]
	v_mfma_f32_16x16x32_bf16 v[134:137], v[206:209], v[36:39], 0
	v_mfma_f32_16x16x32_bf16 v[134:137], v[210:213], v[40:43], v[134:137]
	v_mfma_f32_16x16x32_bf16 v[134:137], v[214:217], v[44:47], v[134:137]
	v_mfma_f32_16x16x32_bf16 v[134:137], v[218:221], v[48:51], v[134:137]
	v_fma_f32 v52, v116, v126, v120
	v_fma_f32 v53, v117, v126, v121
	v_fma_f32 v54, v118, v126, v122
	v_fma_f32 v55, v119, v126, v123
	ds_read_b128 v[190:193], v142 offset:12288
	ds_read_b128 v[194:197], v143 offset:12288
	ds_read_b128 v[198:201], v144 offset:12288
	ds_read_b128 v[202:205], v145 offset:12288
	ds_read_b64 v[206:207], v150 offset:12288
	ds_read_b64 v[208:209], v154 offset:12288
	ds_read_b64 v[210:211], v151 offset:12288
	ds_read_b64 v[212:213], v155 offset:12288
	ds_read_b64 v[214:215], v152 offset:12288
	ds_read_b64 v[216:217], v156 offset:12288
	ds_read_b64 v[218:219], v153 offset:12288
	ds_read_b64 v[220:221], v157 offset:12288
	s_waitcnt lgkmcnt(12)
	v_mfma_f32_16x16x32_bf16 v[116:119], v[158:161], v[20:23], 0
	v_mfma_f32_16x16x32_bf16 v[116:119], v[162:165], v[24:27], v[116:119]
	v_mfma_f32_16x16x32_bf16 v[116:119], v[166:169], v[28:31], v[116:119]
	v_mfma_f32_16x16x32_bf16 v[116:119], v[170:173], v[32:35], v[116:119]
	v_mfma_f32_16x16x32_bf16 v[120:123], v[174:177], v[36:39], 0
	v_mfma_f32_16x16x32_bf16 v[120:123], v[178:181], v[40:43], v[120:123]
	v_mfma_f32_16x16x32_bf16 v[120:123], v[182:185], v[44:47], v[120:123]
	v_mfma_f32_16x16x32_bf16 v[120:123], v[186:189], v[48:51], v[120:123]
	v_fma_f32 v56, v130, v126, v134
	v_fma_f32 v57, v131, v126, v135
	v_fma_f32 v58, v132, v126, v136
	v_fma_f32 v59, v133, v126, v137
	ds_read_b128 v[158:161], v142 offset:16384
	ds_read_b128 v[162:165], v143 offset:16384
	ds_read_b128 v[166:169], v144 offset:16384
	ds_read_b128 v[170:173], v145 offset:16384
	ds_read_b64 v[174:175], v150 offset:16384
	ds_read_b64 v[176:177], v154 offset:16384
	ds_read_b64 v[178:179], v151 offset:16384
	ds_read_b64 v[180:181], v155 offset:16384
	ds_read_b64 v[182:183], v152 offset:16384
	ds_read_b64 v[184:185], v156 offset:16384
	ds_read_b64 v[186:187], v153 offset:16384
	ds_read_b64 v[188:189], v157 offset:16384
	s_waitcnt lgkmcnt(12)
	v_mfma_f32_16x16x32_bf16 v[130:133], v[190:193], v[20:23], 0
	v_mfma_f32_16x16x32_bf16 v[130:133], v[194:197], v[24:27], v[130:133]
	v_mfma_f32_16x16x32_bf16 v[130:133], v[198:201], v[28:31], v[130:133]
	v_mfma_f32_16x16x32_bf16 v[130:133], v[202:205], v[32:35], v[130:133]
	v_mfma_f32_16x16x32_bf16 v[134:137], v[206:209], v[36:39], 0
	v_mfma_f32_16x16x32_bf16 v[134:137], v[210:213], v[40:43], v[134:137]
	v_mfma_f32_16x16x32_bf16 v[134:137], v[214:217], v[44:47], v[134:137]
	v_mfma_f32_16x16x32_bf16 v[134:137], v[218:221], v[48:51], v[134:137]
	v_fma_f32 v60, v116, v126, v120
	v_fma_f32 v61, v117, v126, v121
	v_fma_f32 v62, v118, v126, v122
	v_fma_f32 v63, v119, v126, v123
	ds_read_b128 v[190:193], v142 offset:20480
	ds_read_b128 v[194:197], v143 offset:20480
	ds_read_b128 v[198:201], v144 offset:20480
	ds_read_b128 v[202:205], v145 offset:20480
	ds_read_b64 v[206:207], v150 offset:20480
	ds_read_b64 v[208:209], v154 offset:20480
	ds_read_b64 v[210:211], v151 offset:20480
	ds_read_b64 v[212:213], v155 offset:20480
	ds_read_b64 v[214:215], v152 offset:20480
	ds_read_b64 v[216:217], v156 offset:20480
	ds_read_b64 v[218:219], v153 offset:20480
	ds_read_b64 v[220:221], v157 offset:20480
	s_waitcnt lgkmcnt(12)
	v_mfma_f32_16x16x32_bf16 v[116:119], v[158:161], v[20:23], 0
	v_mfma_f32_16x16x32_bf16 v[116:119], v[162:165], v[24:27], v[116:119]
	v_mfma_f32_16x16x32_bf16 v[116:119], v[166:169], v[28:31], v[116:119]
	v_mfma_f32_16x16x32_bf16 v[116:119], v[170:173], v[32:35], v[116:119]
	v_mfma_f32_16x16x32_bf16 v[120:123], v[174:177], v[36:39], 0
	v_mfma_f32_16x16x32_bf16 v[120:123], v[178:181], v[40:43], v[120:123]
	v_mfma_f32_16x16x32_bf16 v[120:123], v[182:185], v[44:47], v[120:123]
	v_mfma_f32_16x16x32_bf16 v[120:123], v[186:189], v[48:51], v[120:123]
	v_fma_f32 v64, v130, v126, v134
	v_fma_f32 v65, v131, v126, v135
	v_fma_f32 v66, v132, v126, v136
	v_fma_f32 v67, v133, v126, v137
	ds_read_b128 v[158:161], v142 offset:24576
	ds_read_b128 v[162:165], v143 offset:24576
	ds_read_b128 v[166:169], v144 offset:24576
	ds_read_b128 v[170:173], v145 offset:24576
	ds_read_b64 v[174:175], v150 offset:24576
	ds_read_b64 v[176:177], v154 offset:24576
	ds_read_b64 v[178:179], v151 offset:24576
	ds_read_b64 v[180:181], v155 offset:24576
	ds_read_b64 v[182:183], v152 offset:24576
	ds_read_b64 v[184:185], v156 offset:24576
	ds_read_b64 v[186:187], v153 offset:24576
	ds_read_b64 v[188:189], v157 offset:24576
	s_waitcnt lgkmcnt(12)
	v_mfma_f32_16x16x32_bf16 v[130:133], v[190:193], v[20:23], 0
	v_mfma_f32_16x16x32_bf16 v[130:133], v[194:197], v[24:27], v[130:133]
	v_mfma_f32_16x16x32_bf16 v[130:133], v[198:201], v[28:31], v[130:133]
	v_mfma_f32_16x16x32_bf16 v[130:133], v[202:205], v[32:35], v[130:133]
	v_mfma_f32_16x16x32_bf16 v[134:137], v[206:209], v[36:39], 0
	v_mfma_f32_16x16x32_bf16 v[134:137], v[210:213], v[40:43], v[134:137]
	v_mfma_f32_16x16x32_bf16 v[134:137], v[214:217], v[44:47], v[134:137]
	v_mfma_f32_16x16x32_bf16 v[134:137], v[218:221], v[48:51], v[134:137]
	v_fma_f32 v68, v116, v126, v120
	v_fma_f32 v69, v117, v126, v121
	v_fma_f32 v70, v118, v126, v122
	v_fma_f32 v71, v119, v126, v123
	ds_read_b128 v[190:193], v142 offset:28672
	ds_read_b128 v[194:197], v143 offset:28672
	ds_read_b128 v[198:201], v144 offset:28672
	ds_read_b128 v[202:205], v145 offset:28672
	ds_read_b64 v[206:207], v150 offset:28672
	ds_read_b64 v[208:209], v154 offset:28672
	ds_read_b64 v[210:211], v151 offset:28672
	ds_read_b64 v[212:213], v155 offset:28672
	ds_read_b64 v[214:215], v152 offset:28672
	ds_read_b64 v[216:217], v156 offset:28672
	ds_read_b64 v[218:219], v153 offset:28672
	ds_read_b64 v[220:221], v157 offset:28672
	s_waitcnt lgkmcnt(12)
	v_mfma_f32_16x16x32_bf16 v[116:119], v[158:161], v[20:23], 0
	v_mfma_f32_16x16x32_bf16 v[116:119], v[162:165], v[24:27], v[116:119]
	v_mfma_f32_16x16x32_bf16 v[116:119], v[166:169], v[28:31], v[116:119]
	v_mfma_f32_16x16x32_bf16 v[116:119], v[170:173], v[32:35], v[116:119]
	v_mfma_f32_16x16x32_bf16 v[120:123], v[174:177], v[36:39], 0
	v_mfma_f32_16x16x32_bf16 v[120:123], v[178:181], v[40:43], v[120:123]
	v_mfma_f32_16x16x32_bf16 v[120:123], v[182:185], v[44:47], v[120:123]
	v_mfma_f32_16x16x32_bf16 v[120:123], v[186:189], v[48:51], v[120:123]
	v_fma_f32 v72, v130, v126, v134
	v_fma_f32 v73, v131, v126, v135
	v_fma_f32 v74, v132, v126, v136
	v_fma_f32 v75, v133, v126, v137
	ds_read_b128 v[158:161], v142 offset:32768
	ds_read_b128 v[162:165], v143 offset:32768
	ds_read_b128 v[166:169], v144 offset:32768
	ds_read_b128 v[170:173], v145 offset:32768
	ds_read_b64 v[174:175], v150 offset:32768
	ds_read_b64 v[176:177], v154 offset:32768
	ds_read_b64 v[178:179], v151 offset:32768
	ds_read_b64 v[180:181], v155 offset:32768
	ds_read_b64 v[182:183], v152 offset:32768
	ds_read_b64 v[184:185], v156 offset:32768
	ds_read_b64 v[186:187], v153 offset:32768
	ds_read_b64 v[188:189], v157 offset:32768
	s_waitcnt lgkmcnt(12)
	v_mfma_f32_16x16x32_bf16 v[130:133], v[190:193], v[20:23], 0
	v_mfma_f32_16x16x32_bf16 v[130:133], v[194:197], v[24:27], v[130:133]
	v_mfma_f32_16x16x32_bf16 v[130:133], v[198:201], v[28:31], v[130:133]
	v_mfma_f32_16x16x32_bf16 v[130:133], v[202:205], v[32:35], v[130:133]
	v_mfma_f32_16x16x32_bf16 v[134:137], v[206:209], v[36:39], 0
	v_mfma_f32_16x16x32_bf16 v[134:137], v[210:213], v[40:43], v[134:137]
	v_mfma_f32_16x16x32_bf16 v[134:137], v[214:217], v[44:47], v[134:137]
	v_mfma_f32_16x16x32_bf16 v[134:137], v[218:221], v[48:51], v[134:137]
	v_fma_f32 v76, v116, v126, v120
	v_fma_f32 v77, v117, v126, v121
	v_fma_f32 v78, v118, v126, v122
	v_fma_f32 v79, v119, v126, v123
	ds_read_b128 v[190:193], v142 offset:36864
	ds_read_b128 v[194:197], v143 offset:36864
	ds_read_b128 v[198:201], v144 offset:36864
	ds_read_b128 v[202:205], v145 offset:36864
	ds_read_b64 v[206:207], v150 offset:36864
	ds_read_b64 v[208:209], v154 offset:36864
	ds_read_b64 v[210:211], v151 offset:36864
	ds_read_b64 v[212:213], v155 offset:36864
	ds_read_b64 v[214:215], v152 offset:36864
	ds_read_b64 v[216:217], v156 offset:36864
	ds_read_b64 v[218:219], v153 offset:36864
	ds_read_b64 v[220:221], v157 offset:36864
	s_waitcnt lgkmcnt(12)
	v_mfma_f32_16x16x32_bf16 v[116:119], v[158:161], v[20:23], 0
	v_mfma_f32_16x16x32_bf16 v[116:119], v[162:165], v[24:27], v[116:119]
	v_mfma_f32_16x16x32_bf16 v[116:119], v[166:169], v[28:31], v[116:119]
	v_mfma_f32_16x16x32_bf16 v[116:119], v[170:173], v[32:35], v[116:119]
	v_mfma_f32_16x16x32_bf16 v[120:123], v[174:177], v[36:39], 0
	v_mfma_f32_16x16x32_bf16 v[120:123], v[178:181], v[40:43], v[120:123]
	v_mfma_f32_16x16x32_bf16 v[120:123], v[182:185], v[44:47], v[120:123]
	v_mfma_f32_16x16x32_bf16 v[120:123], v[186:189], v[48:51], v[120:123]
	v_fma_f32 v80, v130, v126, v134
	v_fma_f32 v81, v131, v126, v135
	v_fma_f32 v82, v132, v126, v136
	v_fma_f32 v83, v133, v126, v137
	ds_read_b128 v[158:161], v142 offset:40960
	ds_read_b128 v[162:165], v143 offset:40960
	ds_read_b128 v[166:169], v144 offset:40960
	ds_read_b128 v[170:173], v145 offset:40960
	ds_read_b64 v[174:175], v150 offset:40960
	ds_read_b64 v[176:177], v154 offset:40960
	ds_read_b64 v[178:179], v151 offset:40960
	ds_read_b64 v[180:181], v155 offset:40960
	ds_read_b64 v[182:183], v152 offset:40960
	ds_read_b64 v[184:185], v156 offset:40960
	ds_read_b64 v[186:187], v153 offset:40960
	ds_read_b64 v[188:189], v157 offset:40960
	s_waitcnt lgkmcnt(12)
	v_mfma_f32_16x16x32_bf16 v[130:133], v[190:193], v[20:23], 0
	v_mfma_f32_16x16x32_bf16 v[130:133], v[194:197], v[24:27], v[130:133]
	v_mfma_f32_16x16x32_bf16 v[130:133], v[198:201], v[28:31], v[130:133]
	v_mfma_f32_16x16x32_bf16 v[130:133], v[202:205], v[32:35], v[130:133]
	v_mfma_f32_16x16x32_bf16 v[134:137], v[206:209], v[36:39], 0
	v_mfma_f32_16x16x32_bf16 v[134:137], v[210:213], v[40:43], v[134:137]
	v_mfma_f32_16x16x32_bf16 v[134:137], v[214:217], v[44:47], v[134:137]
	v_mfma_f32_16x16x32_bf16 v[134:137], v[218:221], v[48:51], v[134:137]
	v_fma_f32 v84, v116, v126, v120
	v_fma_f32 v85, v117, v126, v121
	v_fma_f32 v86, v118, v126, v122
	v_fma_f32 v87, v119, v126, v123
	ds_read_b128 v[190:193], v142 offset:45056
	ds_read_b128 v[194:197], v143 offset:45056
	ds_read_b128 v[198:201], v144 offset:45056
	ds_read_b128 v[202:205], v145 offset:45056
	ds_read_b64 v[206:207], v150 offset:45056
	ds_read_b64 v[208:209], v154 offset:45056
	ds_read_b64 v[210:211], v151 offset:45056
	ds_read_b64 v[212:213], v155 offset:45056
	ds_read_b64 v[214:215], v152 offset:45056
	ds_read_b64 v[216:217], v156 offset:45056
	ds_read_b64 v[218:219], v153 offset:45056
	ds_read_b64 v[220:221], v157 offset:45056
	s_waitcnt lgkmcnt(12)
	v_mfma_f32_16x16x32_bf16 v[116:119], v[158:161], v[20:23], 0
	v_mfma_f32_16x16x32_bf16 v[116:119], v[162:165], v[24:27], v[116:119]
	v_mfma_f32_16x16x32_bf16 v[116:119], v[166:169], v[28:31], v[116:119]
	v_mfma_f32_16x16x32_bf16 v[116:119], v[170:173], v[32:35], v[116:119]
	v_mfma_f32_16x16x32_bf16 v[120:123], v[174:177], v[36:39], 0
	v_mfma_f32_16x16x32_bf16 v[120:123], v[178:181], v[40:43], v[120:123]
	v_mfma_f32_16x16x32_bf16 v[120:123], v[182:185], v[44:47], v[120:123]
	v_mfma_f32_16x16x32_bf16 v[120:123], v[186:189], v[48:51], v[120:123]
	v_fma_f32 v88, v130, v126, v134
	v_fma_f32 v89, v131, v126, v135
	v_fma_f32 v90, v132, v126, v136
	v_fma_f32 v91, v133, v126, v137
	ds_read_b128 v[158:161], v142 offset:49152
	ds_read_b128 v[162:165], v143 offset:49152
	ds_read_b128 v[166:169], v144 offset:49152
	ds_read_b128 v[170:173], v145 offset:49152
	ds_read_b64 v[174:175], v150 offset:49152
	ds_read_b64 v[176:177], v154 offset:49152
	ds_read_b64 v[178:179], v151 offset:49152
	ds_read_b64 v[180:181], v155 offset:49152
	ds_read_b64 v[182:183], v152 offset:49152
	ds_read_b64 v[184:185], v156 offset:49152
	ds_read_b64 v[186:187], v153 offset:49152
	ds_read_b64 v[188:189], v157 offset:49152
	s_waitcnt lgkmcnt(12)
	v_mfma_f32_16x16x32_bf16 v[130:133], v[190:193], v[20:23], 0
	v_mfma_f32_16x16x32_bf16 v[130:133], v[194:197], v[24:27], v[130:133]
	v_mfma_f32_16x16x32_bf16 v[130:133], v[198:201], v[28:31], v[130:133]
	v_mfma_f32_16x16x32_bf16 v[130:133], v[202:205], v[32:35], v[130:133]
	v_mfma_f32_16x16x32_bf16 v[134:137], v[206:209], v[36:39], 0
	v_mfma_f32_16x16x32_bf16 v[134:137], v[210:213], v[40:43], v[134:137]
	v_mfma_f32_16x16x32_bf16 v[134:137], v[214:217], v[44:47], v[134:137]
	v_mfma_f32_16x16x32_bf16 v[134:137], v[218:221], v[48:51], v[134:137]
	v_fma_f32 v92, v116, v126, v120
	v_fma_f32 v93, v117, v126, v121
	v_fma_f32 v94, v118, v126, v122
	v_fma_f32 v95, v119, v126, v123
	ds_read_b128 v[190:193], v142 offset:53248
	ds_read_b128 v[194:197], v143 offset:53248
	ds_read_b128 v[198:201], v144 offset:53248
	ds_read_b128 v[202:205], v145 offset:53248
	ds_read_b64 v[206:207], v150 offset:53248
	ds_read_b64 v[208:209], v154 offset:53248
	ds_read_b64 v[210:211], v151 offset:53248
	ds_read_b64 v[212:213], v155 offset:53248
	ds_read_b64 v[214:215], v152 offset:53248
	ds_read_b64 v[216:217], v156 offset:53248
	ds_read_b64 v[218:219], v153 offset:53248
	ds_read_b64 v[220:221], v157 offset:53248
	s_waitcnt lgkmcnt(12)
	v_mfma_f32_16x16x32_bf16 v[116:119], v[158:161], v[20:23], 0
	v_mfma_f32_16x16x32_bf16 v[116:119], v[162:165], v[24:27], v[116:119]
	v_mfma_f32_16x16x32_bf16 v[116:119], v[166:169], v[28:31], v[116:119]
	v_mfma_f32_16x16x32_bf16 v[116:119], v[170:173], v[32:35], v[116:119]
	v_mfma_f32_16x16x32_bf16 v[120:123], v[174:177], v[36:39], 0
	v_mfma_f32_16x16x32_bf16 v[120:123], v[178:181], v[40:43], v[120:123]
	v_mfma_f32_16x16x32_bf16 v[120:123], v[182:185], v[44:47], v[120:123]
	v_mfma_f32_16x16x32_bf16 v[120:123], v[186:189], v[48:51], v[120:123]
	v_fma_f32 v96, v130, v126, v134
	v_fma_f32 v97, v131, v126, v135
	v_fma_f32 v98, v132, v126, v136
	v_fma_f32 v99, v133, v126, v137
	ds_read_b128 v[158:161], v142 offset:57344
	ds_read_b128 v[162:165], v143 offset:57344
	ds_read_b128 v[166:169], v144 offset:57344
	ds_read_b128 v[170:173], v145 offset:57344
	ds_read_b64 v[174:175], v150 offset:57344
	ds_read_b64 v[176:177], v154 offset:57344
	ds_read_b64 v[178:179], v151 offset:57344
	ds_read_b64 v[180:181], v155 offset:57344
	ds_read_b64 v[182:183], v152 offset:57344
	ds_read_b64 v[184:185], v156 offset:57344
	ds_read_b64 v[186:187], v153 offset:57344
	ds_read_b64 v[188:189], v157 offset:57344
	s_waitcnt lgkmcnt(12)
	v_mfma_f32_16x16x32_bf16 v[130:133], v[190:193], v[20:23], 0
	v_mfma_f32_16x16x32_bf16 v[130:133], v[194:197], v[24:27], v[130:133]
	v_mfma_f32_16x16x32_bf16 v[130:133], v[198:201], v[28:31], v[130:133]
	v_mfma_f32_16x16x32_bf16 v[130:133], v[202:205], v[32:35], v[130:133]
	v_mfma_f32_16x16x32_bf16 v[134:137], v[206:209], v[36:39], 0
	v_mfma_f32_16x16x32_bf16 v[134:137], v[210:213], v[40:43], v[134:137]
	v_mfma_f32_16x16x32_bf16 v[134:137], v[214:217], v[44:47], v[134:137]
	v_mfma_f32_16x16x32_bf16 v[134:137], v[218:221], v[48:51], v[134:137]
	v_fma_f32 v100, v116, v126, v120
	v_fma_f32 v101, v117, v126, v121
	v_fma_f32 v102, v118, v126, v122
	v_fma_f32 v103, v119, v126, v123
	ds_read_b128 v[190:193], v142 offset:61440
	ds_read_b128 v[194:197], v143 offset:61440
	ds_read_b128 v[198:201], v144 offset:61440
	ds_read_b128 v[202:205], v145 offset:61440
	ds_read_b64 v[206:207], v150 offset:61440
	ds_read_b64 v[208:209], v154 offset:61440
	ds_read_b64 v[210:211], v151 offset:61440
	ds_read_b64 v[212:213], v155 offset:61440
	ds_read_b64 v[214:215], v152 offset:61440
	ds_read_b64 v[216:217], v156 offset:61440
	ds_read_b64 v[218:219], v153 offset:61440
	ds_read_b64 v[220:221], v157 offset:61440
	s_waitcnt lgkmcnt(12)
	v_mfma_f32_16x16x32_bf16 v[116:119], v[158:161], v[20:23], 0
	v_mfma_f32_16x16x32_bf16 v[116:119], v[162:165], v[24:27], v[116:119]
	v_mfma_f32_16x16x32_bf16 v[116:119], v[166:169], v[28:31], v[116:119]
	v_mfma_f32_16x16x32_bf16 v[116:119], v[170:173], v[32:35], v[116:119]
	v_mfma_f32_16x16x32_bf16 v[120:123], v[174:177], v[36:39], 0
	v_mfma_f32_16x16x32_bf16 v[120:123], v[178:181], v[40:43], v[120:123]
	v_mfma_f32_16x16x32_bf16 v[120:123], v[182:185], v[44:47], v[120:123]
	v_mfma_f32_16x16x32_bf16 v[120:123], v[186:189], v[48:51], v[120:123]
	v_fma_f32 v104, v130, v126, v134
	v_fma_f32 v105, v131, v126, v135
	v_fma_f32 v106, v132, v126, v136
	v_fma_f32 v107, v133, v126, v137
	s_waitcnt lgkmcnt(0)
	v_mfma_f32_16x16x32_bf16 v[130:133], v[190:193], v[20:23], 0
	v_mfma_f32_16x16x32_bf16 v[130:133], v[194:197], v[24:27], v[130:133]
	v_mfma_f32_16x16x32_bf16 v[130:133], v[198:201], v[28:31], v[130:133]
	v_mfma_f32_16x16x32_bf16 v[130:133], v[202:205], v[32:35], v[130:133]
	v_mfma_f32_16x16x32_bf16 v[134:137], v[206:209], v[36:39], 0
	v_mfma_f32_16x16x32_bf16 v[134:137], v[210:213], v[40:43], v[134:137]
	v_mfma_f32_16x16x32_bf16 v[134:137], v[214:217], v[44:47], v[134:137]
	v_mfma_f32_16x16x32_bf16 v[134:137], v[218:221], v[48:51], v[134:137]
	v_fma_f32 v108, v116, v126, v120
	v_fma_f32 v109, v117, v126, v121
	v_fma_f32 v110, v118, v126, v122
	v_fma_f32 v111, v119, v126, v123
	s_barrier
	s_nop 7
	v_fma_f32 v112, v130, v126, v134
	v_fma_f32 v113, v131, v126, v135
	v_fma_f32 v114, v132, v126, v136
	v_fma_f32 v115, v133, v126, v137
	v_lshl_or_b32 v117, v1, 2, v2
	v_lshlrev_b32_e32 v117, 2, v117
	v_and_b32_e32 v118, 3, v0
	v_lshrrev_b32_e32 v119, 2, v0
	v_lshl_or_b32 v116, v118, 4, v119
	v_lshlrev_b32_e32 v116, 2, v116
	v_mul_f32_e32 v4, v52, v52
	v_mul_f32_e32 v5, v53, v53
	v_mul_f32_e32 v6, v54, v54
	v_mul_f32_e32 v7, v55, v55
	v_fmac_f32_e32 v4, v56, v56
	v_fmac_f32_e32 v5, v57, v57
	v_fmac_f32_e32 v6, v58, v58
	v_fmac_f32_e32 v7, v59, v59
	v_fmac_f32_e32 v4, v60, v60
	v_fmac_f32_e32 v5, v61, v61
	v_fmac_f32_e32 v6, v62, v62
	v_fmac_f32_e32 v7, v63, v63
	v_fmac_f32_e32 v4, v64, v64
	v_fmac_f32_e32 v5, v65, v65
	v_fmac_f32_e32 v6, v66, v66
	v_fmac_f32_e32 v7, v67, v67
	v_fmac_f32_e32 v4, v68, v68
	v_fmac_f32_e32 v5, v69, v69
	v_fmac_f32_e32 v6, v70, v70
	v_fmac_f32_e32 v7, v71, v71
	v_fmac_f32_e32 v4, v72, v72
	v_fmac_f32_e32 v5, v73, v73
	v_fmac_f32_e32 v6, v74, v74
	v_fmac_f32_e32 v7, v75, v75
	v_fmac_f32_e32 v4, v76, v76
	v_fmac_f32_e32 v5, v77, v77
	v_fmac_f32_e32 v6, v78, v78
	v_fmac_f32_e32 v7, v79, v79
	v_fmac_f32_e32 v4, v80, v80
	v_fmac_f32_e32 v5, v81, v81
	v_fmac_f32_e32 v6, v82, v82
	v_fmac_f32_e32 v7, v83, v83
	v_fmac_f32_e32 v4, v84, v84
	v_fmac_f32_e32 v5, v85, v85
	v_fmac_f32_e32 v6, v86, v86
	v_fmac_f32_e32 v7, v87, v87
	v_fmac_f32_e32 v4, v88, v88
	v_fmac_f32_e32 v5, v89, v89
	v_fmac_f32_e32 v6, v90, v90
	v_fmac_f32_e32 v7, v91, v91
	v_fmac_f32_e32 v4, v92, v92
	v_fmac_f32_e32 v5, v93, v93
	v_fmac_f32_e32 v6, v94, v94
	v_fmac_f32_e32 v7, v95, v95
	v_fmac_f32_e32 v4, v96, v96
	v_fmac_f32_e32 v5, v97, v97
	v_fmac_f32_e32 v6, v98, v98
	v_fmac_f32_e32 v7, v99, v99
	v_fmac_f32_e32 v4, v100, v100
	v_fmac_f32_e32 v5, v101, v101
	v_fmac_f32_e32 v6, v102, v102
	v_fmac_f32_e32 v7, v103, v103
	v_fmac_f32_e32 v4, v104, v104
	v_fmac_f32_e32 v5, v105, v105
	v_fmac_f32_e32 v6, v106, v106
	v_fmac_f32_e32 v7, v107, v107
	v_fmac_f32_e32 v4, v108, v108
	v_fmac_f32_e32 v5, v109, v109
	v_fmac_f32_e32 v6, v110, v110
	v_fmac_f32_e32 v7, v111, v111
	v_fmac_f32_e32 v4, v112, v112
	v_fmac_f32_e32 v5, v113, v113
	v_fmac_f32_e32 v6, v114, v114
	v_fmac_f32_e32 v7, v115, v115
	v_add_f32_e32 v4, v4, v5
	v_add_f32_e32 v6, v6, v7
	v_add_f32_e32 v4, v4, v6
	s_nop 0
	ds_bpermute_b32 v5, v127, v4
	s_waitcnt lgkmcnt(0)
	v_add_f32_e32 v4, v4, v5
	s_nop 0
	ds_bpermute_b32 v5, v11, v4
	s_waitcnt lgkmcnt(0)
	v_add_f32_e32 v4, v4, v5
	v_mul_f32_e32 v4, 0x3b800000, v4
	v_add_f32_e32 v4, 0x358637bd, v4
	v_rsq_f32_e32 v10, v4
	s_waitcnt vmcnt(0)
	ds_bpermute_b32 v222, v117, v222
	ds_bpermute_b32 v223, v117, v223
	ds_bpermute_b32 v224, v117, v224
	ds_bpermute_b32 v225, v117, v225
	ds_bpermute_b32 v226, v117, v226
	ds_bpermute_b32 v227, v117, v227
	ds_bpermute_b32 v228, v117, v228
	ds_bpermute_b32 v229, v117, v229
	ds_bpermute_b32 v230, v117, v230
	ds_bpermute_b32 v231, v117, v231
	ds_bpermute_b32 v232, v117, v232
	ds_bpermute_b32 v233, v117, v233
	s_waitcnt lgkmcnt(0)
	ds_bpermute_b32 v236, v117, v236
	ds_bpermute_b32 v237, v117, v237
	ds_bpermute_b32 v238, v117, v238
	ds_bpermute_b32 v239, v117, v239
	ds_bpermute_b32 v240, v117, v240
	ds_bpermute_b32 v241, v117, v241
	ds_bpermute_b32 v242, v117, v242
	ds_bpermute_b32 v243, v117, v243
	ds_bpermute_b32 v244, v117, v244
	ds_bpermute_b32 v245, v117, v245
	ds_bpermute_b32 v246, v117, v246
	ds_bpermute_b32 v247, v117, v247
	s_waitcnt lgkmcnt(0)
	ds_bpermute_b32 v248, v117, v248
	ds_bpermute_b32 v249, v117, v249
	ds_bpermute_b32 v250, v117, v250
	ds_bpermute_b32 v251, v117, v251
	ds_bpermute_b32 v252, v117, v252
	ds_bpermute_b32 v253, v117, v253
	ds_bpermute_b32 v254, v117, v254
	ds_bpermute_b32 v255, v117, v255
	s_waitcnt lgkmcnt(0)
	v_lshlrev_b32_e32 v4, 16, v222
	v_and_b32_e32 v5, 0xffff0000, v222
	v_lshlrev_b32_e32 v6, 16, v223
	v_and_b32_e32 v7, 0xffff0000, v223
	v_mul_f32_e32 v52, v52, v10
	v_mul_f32_e32 v53, v53, v10
	v_mul_f32_e32 v54, v54, v10
	v_mul_f32_e32 v55, v55, v10
	v_mul_f32_e32 v52, v52, v4
	v_mul_f32_e32 v53, v53, v5
	v_mul_f32_e32 v54, v54, v6
	v_mul_f32_e32 v55, v55, v7
	v_cvt_pk_bf16_f32 v52, v52, v53
	v_cvt_pk_bf16_f32 v53, v54, v55
	v_lshlrev_b32_e32 v4, 16, v224
	v_and_b32_e32 v5, 0xffff0000, v224
	v_lshlrev_b32_e32 v6, 16, v225
	v_and_b32_e32 v7, 0xffff0000, v225
	v_mul_f32_e32 v56, v56, v10
	v_mul_f32_e32 v57, v57, v10
	v_mul_f32_e32 v58, v58, v10
	v_mul_f32_e32 v59, v59, v10
	v_mul_f32_e32 v56, v56, v4
	v_mul_f32_e32 v57, v57, v5
	v_mul_f32_e32 v58, v58, v6
	v_mul_f32_e32 v59, v59, v7
	v_cvt_pk_bf16_f32 v56, v56, v57
	v_cvt_pk_bf16_f32 v57, v58, v59
	v_lshlrev_b32_e32 v4, 16, v226
	v_and_b32_e32 v5, 0xffff0000, v226
	v_lshlrev_b32_e32 v6, 16, v227
	v_and_b32_e32 v7, 0xffff0000, v227
	v_mul_f32_e32 v60, v60, v10
	v_mul_f32_e32 v61, v61, v10
	v_mul_f32_e32 v62, v62, v10
	v_mul_f32_e32 v63, v63, v10
	v_mul_f32_e32 v60, v60, v4
	v_mul_f32_e32 v61, v61, v5
	v_mul_f32_e32 v62, v62, v6
	v_mul_f32_e32 v63, v63, v7
	v_cvt_pk_bf16_f32 v60, v60, v61
	v_cvt_pk_bf16_f32 v61, v62, v63
	v_lshlrev_b32_e32 v4, 16, v228
	v_and_b32_e32 v5, 0xffff0000, v228
	v_lshlrev_b32_e32 v6, 16, v229
	v_and_b32_e32 v7, 0xffff0000, v229
	v_mul_f32_e32 v64, v64, v10
	v_mul_f32_e32 v65, v65, v10
	v_mul_f32_e32 v66, v66, v10
	v_mul_f32_e32 v67, v67, v10
	v_mul_f32_e32 v64, v64, v4
	v_mul_f32_e32 v65, v65, v5
	v_mul_f32_e32 v66, v66, v6
	v_mul_f32_e32 v67, v67, v7
	v_cvt_pk_bf16_f32 v64, v64, v65
	v_cvt_pk_bf16_f32 v65, v66, v67
	v_lshlrev_b32_e32 v4, 16, v230
	v_and_b32_e32 v5, 0xffff0000, v230
	v_lshlrev_b32_e32 v6, 16, v231
	v_and_b32_e32 v7, 0xffff0000, v231
	v_mul_f32_e32 v68, v68, v10
	v_mul_f32_e32 v69, v69, v10
	v_mul_f32_e32 v70, v70, v10
	v_mul_f32_e32 v71, v71, v10
	v_mul_f32_e32 v68, v68, v4
	v_mul_f32_e32 v69, v69, v5
	v_mul_f32_e32 v70, v70, v6
	v_mul_f32_e32 v71, v71, v7
	v_cvt_pk_bf16_f32 v68, v68, v69
	v_cvt_pk_bf16_f32 v69, v70, v71
	v_lshlrev_b32_e32 v4, 16, v232
	v_and_b32_e32 v5, 0xffff0000, v232
	v_lshlrev_b32_e32 v6, 16, v233
	v_and_b32_e32 v7, 0xffff0000, v233
	v_mul_f32_e32 v72, v72, v10
	v_mul_f32_e32 v73, v73, v10
	v_mul_f32_e32 v74, v74, v10
	v_mul_f32_e32 v75, v75, v10
	v_mul_f32_e32 v72, v72, v4
	v_mul_f32_e32 v73, v73, v5
	v_mul_f32_e32 v74, v74, v6
	v_mul_f32_e32 v75, v75, v7
	v_cvt_pk_bf16_f32 v72, v72, v73
	v_cvt_pk_bf16_f32 v73, v74, v75
	v_lshlrev_b32_e32 v4, 16, v236
	v_and_b32_e32 v5, 0xffff0000, v236
	v_lshlrev_b32_e32 v6, 16, v237
	v_and_b32_e32 v7, 0xffff0000, v237
	v_mul_f32_e32 v76, v76, v10
	v_mul_f32_e32 v77, v77, v10
	v_mul_f32_e32 v78, v78, v10
	v_mul_f32_e32 v79, v79, v10
	v_mul_f32_e32 v76, v76, v4
	v_mul_f32_e32 v77, v77, v5
	v_mul_f32_e32 v78, v78, v6
	v_mul_f32_e32 v79, v79, v7
	v_cvt_pk_bf16_f32 v76, v76, v77
	v_cvt_pk_bf16_f32 v77, v78, v79
	v_lshlrev_b32_e32 v4, 16, v238
	v_and_b32_e32 v5, 0xffff0000, v238
	v_lshlrev_b32_e32 v6, 16, v239
	v_and_b32_e32 v7, 0xffff0000, v239
	v_mul_f32_e32 v80, v80, v10
	v_mul_f32_e32 v81, v81, v10
	v_mul_f32_e32 v82, v82, v10
	v_mul_f32_e32 v83, v83, v10
	v_mul_f32_e32 v80, v80, v4
	v_mul_f32_e32 v81, v81, v5
	v_mul_f32_e32 v82, v82, v6
	v_mul_f32_e32 v83, v83, v7
	v_cvt_pk_bf16_f32 v80, v80, v81
	v_cvt_pk_bf16_f32 v81, v82, v83
	v_lshlrev_b32_e32 v4, 16, v240
	v_and_b32_e32 v5, 0xffff0000, v240
	v_lshlrev_b32_e32 v6, 16, v241
	v_and_b32_e32 v7, 0xffff0000, v241
	v_mul_f32_e32 v84, v84, v10
	v_mul_f32_e32 v85, v85, v10
	v_mul_f32_e32 v86, v86, v10
	v_mul_f32_e32 v87, v87, v10
	v_mul_f32_e32 v84, v84, v4
	v_mul_f32_e32 v85, v85, v5
	v_mul_f32_e32 v86, v86, v6
	v_mul_f32_e32 v87, v87, v7
	v_cvt_pk_bf16_f32 v84, v84, v85
	v_cvt_pk_bf16_f32 v85, v86, v87
	v_lshlrev_b32_e32 v4, 16, v242
	v_and_b32_e32 v5, 0xffff0000, v242
	v_lshlrev_b32_e32 v6, 16, v243
	v_and_b32_e32 v7, 0xffff0000, v243
	v_mul_f32_e32 v88, v88, v10
	v_mul_f32_e32 v89, v89, v10
	v_mul_f32_e32 v90, v90, v10
	v_mul_f32_e32 v91, v91, v10
	v_mul_f32_e32 v88, v88, v4
	v_mul_f32_e32 v89, v89, v5
	v_mul_f32_e32 v90, v90, v6
	v_mul_f32_e32 v91, v91, v7
	v_cvt_pk_bf16_f32 v88, v88, v89
	v_cvt_pk_bf16_f32 v89, v90, v91
	v_lshlrev_b32_e32 v4, 16, v244
	v_and_b32_e32 v5, 0xffff0000, v244
	v_lshlrev_b32_e32 v6, 16, v245
	v_and_b32_e32 v7, 0xffff0000, v245
	v_mul_f32_e32 v92, v92, v10
	v_mul_f32_e32 v93, v93, v10
	v_mul_f32_e32 v94, v94, v10
	v_mul_f32_e32 v95, v95, v10
	v_mul_f32_e32 v92, v92, v4
	v_mul_f32_e32 v93, v93, v5
	v_mul_f32_e32 v94, v94, v6
	v_mul_f32_e32 v95, v95, v7
	v_cvt_pk_bf16_f32 v92, v92, v93
	v_cvt_pk_bf16_f32 v93, v94, v95
	v_lshlrev_b32_e32 v4, 16, v246
	v_and_b32_e32 v5, 0xffff0000, v246
	v_lshlrev_b32_e32 v6, 16, v247
	v_and_b32_e32 v7, 0xffff0000, v247
	v_mul_f32_e32 v96, v96, v10
	v_mul_f32_e32 v97, v97, v10
	v_mul_f32_e32 v98, v98, v10
	v_mul_f32_e32 v99, v99, v10
	v_mul_f32_e32 v96, v96, v4
	v_mul_f32_e32 v97, v97, v5
	v_mul_f32_e32 v98, v98, v6
	v_mul_f32_e32 v99, v99, v7
	v_cvt_pk_bf16_f32 v96, v96, v97
	v_cvt_pk_bf16_f32 v97, v98, v99
	v_lshlrev_b32_e32 v4, 16, v248
	v_and_b32_e32 v5, 0xffff0000, v248
	v_lshlrev_b32_e32 v6, 16, v249
	v_and_b32_e32 v7, 0xffff0000, v249
	v_mul_f32_e32 v100, v100, v10
	v_mul_f32_e32 v101, v101, v10
	v_mul_f32_e32 v102, v102, v10
	v_mul_f32_e32 v103, v103, v10
	v_mul_f32_e32 v100, v100, v4
	v_mul_f32_e32 v101, v101, v5
	v_mul_f32_e32 v102, v102, v6
	v_mul_f32_e32 v103, v103, v7
	v_cvt_pk_bf16_f32 v100, v100, v101
	v_cvt_pk_bf16_f32 v101, v102, v103
	v_lshlrev_b32_e32 v4, 16, v250
	v_and_b32_e32 v5, 0xffff0000, v250
	v_lshlrev_b32_e32 v6, 16, v251
	v_and_b32_e32 v7, 0xffff0000, v251
	v_mul_f32_e32 v104, v104, v10
	v_mul_f32_e32 v105, v105, v10
	v_mul_f32_e32 v106, v106, v10
	v_mul_f32_e32 v107, v107, v10
	v_mul_f32_e32 v104, v104, v4
	v_mul_f32_e32 v105, v105, v5
	v_mul_f32_e32 v106, v106, v6
	v_mul_f32_e32 v107, v107, v7
	v_cvt_pk_bf16_f32 v104, v104, v105
	v_cvt_pk_bf16_f32 v105, v106, v107
	v_lshlrev_b32_e32 v4, 16, v252
	v_and_b32_e32 v5, 0xffff0000, v252
	v_lshlrev_b32_e32 v6, 16, v253
	v_and_b32_e32 v7, 0xffff0000, v253
	v_mul_f32_e32 v108, v108, v10
	v_mul_f32_e32 v109, v109, v10
	v_mul_f32_e32 v110, v110, v10
	v_mul_f32_e32 v111, v111, v10
	v_mul_f32_e32 v108, v108, v4
	v_mul_f32_e32 v109, v109, v5
	v_mul_f32_e32 v110, v110, v6
	v_mul_f32_e32 v111, v111, v7
	v_cvt_pk_bf16_f32 v108, v108, v109
	v_cvt_pk_bf16_f32 v109, v110, v111
	v_lshlrev_b32_e32 v4, 16, v254
	v_and_b32_e32 v5, 0xffff0000, v254
	v_lshlrev_b32_e32 v6, 16, v255
	v_and_b32_e32 v7, 0xffff0000, v255
	v_mul_f32_e32 v112, v112, v10
	v_mul_f32_e32 v113, v113, v10
	v_mul_f32_e32 v114, v114, v10
	v_mul_f32_e32 v115, v115, v10
	v_mul_f32_e32 v112, v112, v4
	v_mul_f32_e32 v113, v113, v5
	v_mul_f32_e32 v114, v114, v6
	v_mul_f32_e32 v115, v115, v7
	v_cvt_pk_bf16_f32 v112, v112, v113
	v_cvt_pk_bf16_f32 v113, v114, v115
	ds_bpermute_b32 v52, v116, v52
	ds_bpermute_b32 v53, v116, v53
	ds_bpermute_b32 v56, v116, v56
	ds_bpermute_b32 v57, v116, v57
	ds_bpermute_b32 v60, v116, v60
	ds_bpermute_b32 v61, v116, v61
	ds_bpermute_b32 v64, v116, v64
	ds_bpermute_b32 v65, v116, v65
	ds_bpermute_b32 v68, v116, v68
	ds_bpermute_b32 v69, v116, v69
	ds_bpermute_b32 v72, v116, v72
	ds_bpermute_b32 v73, v116, v73
	s_waitcnt lgkmcnt(0)
	ds_bpermute_b32 v76, v116, v76
	ds_bpermute_b32 v77, v116, v77
	ds_bpermute_b32 v80, v116, v80
	ds_bpermute_b32 v81, v116, v81
	ds_bpermute_b32 v84, v116, v84
	ds_bpermute_b32 v85, v116, v85
	ds_bpermute_b32 v88, v116, v88
	ds_bpermute_b32 v89, v116, v89
	ds_bpermute_b32 v92, v116, v92
	ds_bpermute_b32 v93, v116, v93
	ds_bpermute_b32 v96, v116, v96
	ds_bpermute_b32 v97, v116, v97
	s_waitcnt lgkmcnt(0)
	ds_bpermute_b32 v100, v116, v100
	ds_bpermute_b32 v101, v116, v101
	ds_bpermute_b32 v104, v116, v104
	ds_bpermute_b32 v105, v116, v105
	ds_bpermute_b32 v108, v116, v108
	ds_bpermute_b32 v109, v116, v109
	ds_bpermute_b32 v112, v116, v112
	ds_bpermute_b32 v113, v116, v113
	s_waitcnt lgkmcnt(0)
	global_store_dwordx2 v124, v[52:53], s[74:75] offset:0
	global_store_dwordx2 v124, v[56:57], s[74:75] offset:32
	global_store_dwordx2 v124, v[60:61], s[74:75] offset:64
	global_store_dwordx2 v124, v[64:65], s[74:75] offset:96
	global_store_dwordx2 v124, v[68:69], s[74:75] offset:128
	global_store_dwordx2 v124, v[72:73], s[74:75] offset:160
	global_store_dwordx2 v124, v[76:77], s[74:75] offset:192
	global_store_dwordx2 v124, v[80:81], s[74:75] offset:224
	global_store_dwordx2 v124, v[84:85], s[74:75] offset:256
	global_store_dwordx2 v124, v[88:89], s[74:75] offset:288
	global_store_dwordx2 v124, v[92:93], s[74:75] offset:320
	global_store_dwordx2 v124, v[96:97], s[74:75] offset:352
	global_store_dwordx2 v124, v[100:101], s[74:75] offset:384
	global_store_dwordx2 v124, v[104:105], s[74:75] offset:416
	global_store_dwordx2 v124, v[108:109], s[74:75] offset:448
	global_store_dwordx2 v124, v[112:113], s[74:75] offset:480
	s_add_u32 s64, s64, s94
	s_cmp_lt_u32 s64, 0x200
	s_cbranch_scc1 .LR3_unit

.LBB0_1830:
	s_mov_b64 s[80:81], exec
	s_mov_b64 exec, 1
	v_mov_b32_e32 v237, 1
	global_atomic_add v237, v236, v237, s[50:51] sc0
	s_mov_b64 exec, s[80:81]
	global_load_dwordx4 v[28:31], v[70:71], off offset:-4096 nt
	global_load_dwordx4 v[24:27], v[70:71], off offset:-3072 nt
	global_load_dwordx4 v[20:23], v[70:71], off offset:-2048 nt
	global_load_dwordx4 v[16:19], v[70:71], off offset:-1024 nt
	global_load_dwordx4 v[12:15], v[70:71], off nt
	global_load_dwordx4 v[8:11], v[70:71], off offset:1024 nt
	global_load_dwordx4 v[4:7], v[70:71], off offset:2048 nt
	global_load_dwordx4 v[0:3], v[70:71], off offset:3072 nt
	v_add_u32_e32 v33, 0xffffe000, v64
	v_lshrrev_b32_e32 v33, 3, v33
	v_ashrrev_i32_e32 v32, 12, v64
	v_add_u32_e32 v33, 2, v33
	v_cmp_gt_i32_e32 vcc, s1, v64
	s_nop 1
	v_cndmask_b32_e32 v32, v33, v32, vcc
	v_mad_i64_i32 v[32:33], s[16:17], v32, s10, v[72:73]
	v_add_co_u32_e32 v50, vcc, s11, v68
	v_lshl_add_u64 v[48:49], v[32:33], 0, s[8:9]
	s_nop 0
	v_addc_co_u32_e32 v51, vcc, -1, v69, vcc
	v_add_co_u32_e32 v60, vcc, s12, v68
	v_lshl_add_u64 v[40:41], v[48:49], 0, v[66:67]
	s_nop 0
	v_addc_co_u32_e32 v61, vcc, -1, v69, vcc
	v_add_co_u32_e32 v62, vcc, s13, v68
	v_lshl_add_u64 v[42:43], v[48:49], 0, v[74:75]
	v_lshl_add_u64 v[52:53], v[48:49], 0, v[76:77]
	v_lshl_add_u64 v[54:55], v[48:49], 0, v[78:79]
	v_addc_co_u32_e32 v63, vcc, -1, v69, vcc
	global_load_dwordx4 v[36:39], v[40:41], off
	global_load_dwordx4 v[32:35], v[42:43], off
	global_load_dwordx2 v[90:91], v[50:51], off offset:-3584 nt
	global_load_dwordx2 v[102:103], v[50:51], off offset:-3072 nt
	global_load_dwordx2 v[114:115], v[50:51], off offset:-2560 nt
	global_load_dwordx2 v[126:127], v[50:51], off offset:-2048 nt
	global_load_dwordx2 v[100:101], v[60:61], off offset:-3584 nt
	global_load_dwordx2 v[112:113], v[60:61], off offset:-3072 nt
	global_load_dwordx2 v[116:117], v[60:61], off offset:-2560 nt
	global_load_dwordx2 v[128:129], v[60:61], off offset:-2048 nt
	global_load_dwordx2 v[136:137], v[62:63], off offset:-3584 nt
	global_load_dwordx2 v[138:139], v[62:63], off offset:-3072 nt
	global_load_dwordx2 v[140:141], v[62:63], off offset:-2560 nt
	global_load_dwordx2 v[142:143], v[62:63], off offset:-2048 nt
	global_load_dwordx2 v[144:145], v[68:69], off offset:-3584 nt
	global_load_dwordx2 v[146:147], v[68:69], off offset:-3072 nt
	global_load_dwordx2 v[148:149], v[68:69], off offset:-2560 nt
	global_load_dwordx2 v[150:151], v[68:69], off offset:-2048 nt
	global_load_dwordx4 v[44:47], v[52:53], off
	global_load_dwordx4 v[40:43], v[54:55], off
	v_lshl_add_u64 v[52:53], v[48:49], 0, v[80:81]
	v_lshl_add_u64 v[54:55], v[48:49], 0, v[82:83]
	global_load_dwordx4 v[56:59], v[52:53], off
	s_nop 0
	global_load_dwordx4 v[52:55], v[54:55], off
	s_nop 0
	global_load_dwordx2 v[152:153], v[50:51], off offset:-1536 nt
	global_load_dwordx2 v[118:119], v[50:51], off offset:-1024 nt
	global_load_dwordx2 v[104:105], v[50:51], off offset:-512 nt
	global_load_dwordx2 v[96:97], v[50:51], off nt
	global_load_dwordx2 v[154:155], v[60:61], off offset:-1536 nt
	global_load_dwordx2 v[124:125], v[60:61], off offset:-1024 nt
	global_load_dwordx2 v[110:111], v[60:61], off offset:-512 nt
	global_load_dwordx2 v[98:99], v[60:61], off nt
	global_load_dwordx2 v[156:157], v[62:63], off offset:-1536 nt
	global_load_dwordx2 v[120:121], v[62:63], off offset:-1024 nt
	global_load_dwordx2 v[106:107], v[62:63], off offset:-512 nt
	global_load_dwordx2 v[92:93], v[62:63], off nt
	global_load_dwordx2 v[158:159], v[68:69], off offset:-1536 nt
	global_load_dwordx2 v[122:123], v[68:69], off offset:-1024 nt
	global_load_dwordx2 v[108:109], v[68:69], off offset:-512 nt
	global_load_dwordx2 v[94:95], v[68:69], off nt
	v_lshl_add_u64 v[88:89], v[48:49], 0, v[84:85]
	v_lshl_add_u64 v[48:49], v[48:49], 0, v[86:87]
	global_load_dwordx4 v[60:63], v[88:89], off
	s_nop 0
	global_load_dwordx4 v[48:51], v[48:49], off
	s_waitcnt vmcnt(37)
	v_lshlrev_b32_e32 v88, 16, v90
	v_and_b32_e32 v89, 0xffff0000, v90
	s_waitcnt vmcnt(33)
	v_lshlrev_b32_e32 v160, 16, v100
	v_and_b32_e32 v161, 0xffff0000, v100
	v_lshlrev_b32_e32 v90, 16, v91
	v_and_b32_e32 v91, 0xffff0000, v91
	v_lshlrev_b32_e32 v100, 16, v101
	v_and_b32_e32 v101, 0xffff0000, v101
	v_pk_add_f32 v[88:89], v[88:89], v[160:161]
	s_waitcnt vmcnt(29)
	v_lshlrev_b32_e32 v160, 16, v136
	v_and_b32_e32 v161, 0xffff0000, v136
	v_pk_add_f32 v[90:91], v[90:91], v[100:101]
	v_lshlrev_b32_e32 v100, 16, v137
	v_and_b32_e32 v101, 0xffff0000, v137
	s_waitcnt vmcnt(25)
	v_lshlrev_b32_e32 v136, 16, v145
	v_and_b32_e32 v137, 0xffff0000, v145
	v_pk_add_f32 v[100:101], v[100:101], v[136:137]
	v_lshlrev_b32_e32 v136, 16, v112
	v_pk_add_f32 v[90:91], v[90:91], v[100:101]
	v_lshlrev_b32_e32 v100, 16, v102
	v_and_b32_e32 v101, 0xffff0000, v102
	v_and_b32_e32 v137, 0xffff0000, v112
	v_lshlrev_b32_e32 v162, 16, v144
	v_and_b32_e32 v163, 0xffff0000, v144
	v_pk_add_f32 v[100:101], v[100:101], v[136:137]
	v_lshlrev_b32_e32 v136, 16, v138
	v_and_b32_e32 v137, 0xffff0000, v138
	s_waitcnt vmcnt(24)
	v_lshlrev_b32_e32 v144, 16, v146
	v_and_b32_e32 v145, 0xffff0000, v146
	v_pk_add_f32 v[136:137], v[136:137], v[144:145]
	v_lshlrev_b32_e32 v102, 16, v103
	v_and_b32_e32 v103, 0xffff0000, v103
	v_lshlrev_b32_e32 v112, 16, v113
	v_and_b32_e32 v113, 0xffff0000, v113
	v_pk_add_f32 v[160:161], v[160:161], v[162:163]
	v_pk_add_f32 v[100:101], v[100:101], v[136:137]
	v_pk_add_f32 v[102:103], v[102:103], v[112:113]
	v_lshlrev_b32_e32 v112, 16, v139
	v_and_b32_e32 v113, 0xffff0000, v139
	v_lshlrev_b32_e32 v136, 16, v147
	v_and_b32_e32 v137, 0xffff0000, v147
	v_pk_add_f32 v[88:89], v[88:89], v[160:161]
	v_pk_add_f32 v[112:113], v[112:113], v[136:137]
	v_mov_b32_e32 v136, v89
	v_pk_add_f32 v[102:103], v[102:103], v[112:113]
	v_mov_b32_e32 v137, v101
	v_mov_b32_e32 v112, v88
	v_mov_b32_e32 v113, v100
	v_pk_mul_f32 v[136:137], v[136:137], v[136:137]
	v_mov_b32_e32 v138, v91
	v_mov_b32_e32 v139, v103
	v_pk_fma_f32 v[112:113], v[112:113], v[112:113], v[136:137]
	v_mov_b32_e32 v136, v90
	v_mov_b32_e32 v137, v102
	v_pk_mul_f32 v[138:139], v[138:139], v[138:139]
	s_waitcnt vmcnt(23)
	v_lshlrev_b32_e32 v144, 16, v148
	v_pk_fma_f32 v[136:137], v[136:137], v[136:137], v[138:139]
	v_lshlrev_b32_e32 v138, 16, v116
	v_pk_add_f32 v[112:113], v[112:113], v[136:137]
	v_and_b32_e32 v139, 0xffff0000, v116
	v_pk_add_f32 v[136:137], v[112:113], v[112:113] op_sel:[0,1] op_sel_hi:[1,0]
	v_lshlrev_b32_e32 v112, 16, v114
	v_and_b32_e32 v113, 0xffff0000, v114
	v_pk_add_f32 v[112:113], v[112:113], v[138:139]
	v_lshlrev_b32_e32 v138, 16, v140
	v_and_b32_e32 v139, 0xffff0000, v140
	v_and_b32_e32 v145, 0xffff0000, v148
	v_pk_add_f32 v[138:139], v[138:139], v[144:145]
	v_lshlrev_b32_e32 v114, 16, v115
	v_and_b32_e32 v115, 0xffff0000, v115
	v_lshlrev_b32_e32 v116, 16, v117
	v_and_b32_e32 v117, 0xffff0000, v117
	v_pk_add_f32 v[112:113], v[112:113], v[138:139]
	v_pk_add_f32 v[114:115], v[114:115], v[116:117]
	v_lshlrev_b32_e32 v116, 16, v141
	v_and_b32_e32 v117, 0xffff0000, v141
	v_lshlrev_b32_e32 v138, 16, v149
	v_and_b32_e32 v139, 0xffff0000, v149
	v_pk_add_f32 v[116:117], v[116:117], v[138:139]
	v_mov_b32_e32 v138, v113
	v_pk_add_f32 v[114:115], v[114:115], v[116:117]
	v_mov_b32_e32 v116, v112
	v_mov_b32_e32 v139, v115
	v_mov_b32_e32 v117, v114
	v_pk_mul_f32 v[138:139], v[138:139], v[138:139]
	v_lshlrev_b32_e32 v140, 16, v128
	v_pk_fma_f32 v[116:117], v[116:117], v[116:117], v[138:139]
	v_and_b32_e32 v141, 0xffff0000, v128
	v_pk_add_f32 v[138:139], v[116:117], v[116:117] op_sel:[0,1] op_sel_hi:[1,0]
	v_lshlrev_b32_e32 v116, 16, v126
	v_and_b32_e32 v117, 0xffff0000, v126
	v_pk_add_f32 v[116:117], v[116:117], v[140:141]
	v_lshlrev_b32_e32 v140, 16, v142
	v_and_b32_e32 v141, 0xffff0000, v142
	s_waitcnt vmcnt(22)
	v_lshlrev_b32_e32 v144, 16, v150
	v_and_b32_e32 v145, 0xffff0000, v150
	v_pk_add_f32 v[140:141], v[140:141], v[144:145]
	v_lshlrev_b32_e32 v126, 16, v127
	v_and_b32_e32 v127, 0xffff0000, v127
	v_lshlrev_b32_e32 v128, 16, v129
	v_and_b32_e32 v129, 0xffff0000, v129
	v_pk_add_f32 v[116:117], v[116:117], v[140:141]
	v_pk_add_f32 v[126:127], v[126:127], v[128:129]
	v_lshlrev_b32_e32 v128, 16, v143
	v_and_b32_e32 v129, 0xffff0000, v143
	v_lshlrev_b32_e32 v140, 16, v151
	v_and_b32_e32 v141, 0xffff0000, v151
	v_pk_add_f32 v[128:129], v[128:129], v[140:141]
	s_waitcnt vmcnt(13)
	v_lshlrev_b32_e32 v144, 16, v154
	v_pk_add_f32 v[126:127], v[126:127], v[128:129]
	v_mul_f32_e32 v128, v117, v117
	v_pk_fma_f32 v[140:141], v[116:117], v[116:117], v[128:129] op_sel_hi:[1,1,0]
	v_mul_f32_e32 v128, v127, v127
	v_pk_fma_f32 v[142:143], v[126:127], v[126:127], v[128:129] op_sel_hi:[1,1,0]
	v_lshlrev_b32_e32 v128, 16, v152
	v_and_b32_e32 v129, 0xffff0000, v152
	v_and_b32_e32 v145, 0xffff0000, v154
	v_pk_add_f32 v[128:129], v[128:129], v[144:145]
	s_waitcnt vmcnt(9)
	v_lshlrev_b32_e32 v144, 16, v156
	v_and_b32_e32 v145, 0xffff0000, v156
	s_waitcnt vmcnt(5)
	v_lshlrev_b32_e32 v146, 16, v158
	v_and_b32_e32 v147, 0xffff0000, v158
	v_pk_add_f32 v[144:145], v[144:145], v[146:147]
	v_lshlrev_b32_e32 v146, 16, v155
	v_pk_add_f32 v[128:129], v[128:129], v[144:145]
	v_lshlrev_b32_e32 v144, 16, v153
	v_and_b32_e32 v145, 0xffff0000, v153
	v_and_b32_e32 v147, 0xffff0000, v155
	v_pk_add_f32 v[144:145], v[144:145], v[146:147]
	v_lshlrev_b32_e32 v146, 16, v157
	v_and_b32_e32 v147, 0xffff0000, v157
	v_lshlrev_b32_e32 v148, 16, v159
	v_and_b32_e32 v149, 0xffff0000, v159
	v_pk_add_f32 v[146:147], v[146:147], v[148:149]
	s_nop 0
	v_pk_add_f32 v[144:145], v[144:145], v[146:147]
	v_pk_mul_f32 v[146:147], v[128:129], v[128:129]
	v_pk_mul_f32 v[148:149], v[144:145], v[144:145]
	v_mov_b32_e32 v137, v146
	v_mov_b32_e32 v139, v147
	v_mov_b32_e32 v141, v148
	v_mov_b32_e32 v143, v149
	v_pk_add_f32 v[136:137], v[136:137], v[138:139]
	v_pk_add_f32 v[138:139], v[140:141], v[142:143]
	v_lshlrev_b32_e32 v140, 16, v124
	v_pk_add_f32 v[136:137], v[136:137], v[138:139]
	v_lshlrev_b32_e32 v138, 16, v118
	v_and_b32_e32 v139, 0xffff0000, v118
	v_and_b32_e32 v141, 0xffff0000, v124
	v_pk_add_f32 v[138:139], v[138:139], v[140:141]
	v_lshlrev_b32_e32 v140, 16, v120
	v_and_b32_e32 v141, 0xffff0000, v120
	s_waitcnt vmcnt(4)
	v_lshlrev_b32_e32 v142, 16, v122
	v_and_b32_e32 v143, 0xffff0000, v122
	v_lshlrev_b32_e32 v118, 16, v119
	v_and_b32_e32 v119, 0xffff0000, v119
	v_lshlrev_b32_e32 v124, 16, v125
	v_and_b32_e32 v125, 0xffff0000, v125
	v_lshlrev_b32_e32 v120, 16, v121
	v_and_b32_e32 v121, 0xffff0000, v121
	v_lshlrev_b32_e32 v122, 16, v123
	v_and_b32_e32 v123, 0xffff0000, v123
	v_pk_add_f32 v[140:141], v[140:141], v[142:143]
	v_pk_add_f32 v[118:119], v[118:119], v[124:125]
	v_pk_add_f32 v[120:121], v[120:121], v[122:123]
	v_pk_add_f32 v[138:139], v[138:139], v[140:141]
	v_pk_add_f32 v[118:119], v[118:119], v[120:121]
	v_mov_b32_e32 v122, v139
	v_mov_b32_e32 v123, v119
	v_mov_b32_e32 v120, v138
	v_mov_b32_e32 v121, v118
	v_pk_mul_f32 v[122:123], v[122:123], v[122:123]
	v_lshlrev_b32_e32 v124, 16, v110
	v_pk_fma_f32 v[120:121], v[120:121], v[120:121], v[122:123]
	v_lshlrev_b32_e32 v122, 16, v104
	v_and_b32_e32 v123, 0xffff0000, v104
	v_and_b32_e32 v125, 0xffff0000, v110
	v_pk_add_f32 v[122:123], v[122:123], v[124:125]
	v_lshlrev_b32_e32 v124, 16, v106
	v_and_b32_e32 v125, 0xffff0000, v106
	s_waitcnt vmcnt(3)
	v_lshlrev_b32_e32 v140, 16, v108
	v_and_b32_e32 v141, 0xffff0000, v108
	v_pk_add_f32 v[124:125], v[124:125], v[140:141]
	v_lshlrev_b32_e32 v104, 16, v105
	v_and_b32_e32 v105, 0xffff0000, v105
	v_lshlrev_b32_e32 v110, 16, v111
	v_and_b32_e32 v111, 0xffff0000, v111
	v_pk_add_f32 v[122:123], v[122:123], v[124:125]
	v_pk_add_f32 v[104:105], v[104:105], v[110:111]
	v_lshlrev_b32_e32 v106, 16, v107
	v_and_b32_e32 v107, 0xffff0000, v107
	v_lshlrev_b32_e32 v108, 16, v109
	v_and_b32_e32 v109, 0xffff0000, v109
	v_lshlrev_b32_e32 v110, 16, v96
	v_and_b32_e32 v111, 0xffff0000, v96
	v_lshlrev_b32_e32 v124, 16, v98
	v_and_b32_e32 v125, 0xffff0000, v98
	v_pk_add_f32 v[106:107], v[106:107], v[108:109]
	v_pk_add_f32 v[110:111], v[110:111], v[124:125]
	v_lshlrev_b32_e32 v124, 16, v92
	v_and_b32_e32 v125, 0xffff0000, v92
	s_waitcnt vmcnt(2)
	v_lshlrev_b32_e32 v140, 16, v94
	v_and_b32_e32 v141, 0xffff0000, v94
	v_lshlrev_b32_e32 v96, 16, v97
	v_and_b32_e32 v97, 0xffff0000, v97
	v_lshlrev_b32_e32 v98, 16, v99
	v_and_b32_e32 v99, 0xffff0000, v99
	v_lshlrev_b32_e32 v92, 16, v93
	v_and_b32_e32 v93, 0xffff0000, v93
	v_lshlrev_b32_e32 v94, 16, v95
	v_and_b32_e32 v95, 0xffff0000, v95
	v_pk_add_f32 v[104:105], v[104:105], v[106:107]
	v_pk_add_f32 v[124:125], v[124:125], v[140:141]
	v_pk_add_f32 v[96:97], v[96:97], v[98:99]
	v_pk_add_f32 v[92:93], v[92:93], v[94:95]
	v_mul_f32_e32 v106, v123, v123
	v_mul_f32_e32 v108, v105, v105
	v_pk_add_f32 v[110:111], v[110:111], v[124:125]
	v_pk_add_f32 v[92:93], v[96:97], v[92:93]
	v_pk_add_f32 v[136:137], v[136:137], v[136:137] op_sel:[0,1] op_sel_hi:[1,0]
	v_pk_add_f32 v[120:121], v[120:121], v[120:121] op_sel:[0,1] op_sel_hi:[1,0]
	v_pk_fma_f32 v[106:107], v[122:123], v[122:123], v[106:107] op_sel_hi:[1,1,0]
	v_pk_fma_f32 v[108:109], v[104:105], v[104:105], v[108:109] op_sel_hi:[1,1,0]
	v_pk_mul_f32 v[94:95], v[110:111], v[110:111]
	v_pk_mul_f32 v[96:97], v[92:93], v[92:93]
	v_mov_b32_e32 v137, v94
	v_mov_b32_e32 v121, v95
	v_mov_b32_e32 v107, v96
	v_mov_b32_e32 v109, v97
	v_pk_add_f32 v[94:95], v[136:137], v[120:121]
	v_pk_add_f32 v[96:97], v[106:107], v[108:109]
	s_nop 0
	v_pk_add_f32 v[94:95], v[94:95], v[96:97]
	s_nop 0
	v_add_f32_e32 v94, v94, v95
	ds_bpermute_b32 v95, v130, v94
	s_waitcnt lgkmcnt(0)
	v_add_f32_e32 v94, v94, v95
	ds_bpermute_b32 v95, v131, v94
	s_waitcnt lgkmcnt(0)
	v_add_f32_e32 v94, v94, v95
	ds_bpermute_b32 v95, v132, v94
	s_waitcnt lgkmcnt(0)
	v_add_f32_e32 v94, v94, v95
	ds_bpermute_b32 v95, v133, v94
	s_waitcnt lgkmcnt(0)
	v_add_f32_e32 v94, v94, v95
	ds_bpermute_b32 v95, v134, v94
	s_waitcnt lgkmcnt(0)
	v_add_f32_e32 v94, v94, v95
	ds_bpermute_b32 v95, v135, v94
	s_waitcnt lgkmcnt(0)
	v_add_f32_e32 v94, v94, v95
	v_fmamk_f32 v94, v94, 0x3a000000, v65
	v_mul_f32_e32 v95, 0x4b800000, v94
	v_cmp_gt_f32_e32 vcc, s14, v94
	s_nop 1
	v_cndmask_b32_e32 v94, v94, v95, vcc
	v_rsq_f32_e32 v94, v94
	s_nop 0
	v_mul_f32_e32 v95, 0x45800000, v94
	v_cndmask_b32_e32 v94, v94, v95, vcc
	v_pk_mul_f32 v[88:89], v[88:89], v[94:95] op_sel_hi:[1,0]
	v_pk_mul_f32 v[90:91], v[90:91], v[94:95] op_sel_hi:[1,0]
	v_pk_mul_f32 v[106:107], v[116:117], v[94:95] op_sel_hi:[1,0]
	v_pk_mul_f32 v[116:117], v[138:139], v[94:95] op_sel_hi:[1,0]
	v_pk_mul_f32 v[118:119], v[118:119], v[94:95] op_sel_hi:[1,0]
	v_pk_mul_f32 v[96:97], v[100:101], v[94:95] op_sel_hi:[1,0]
	v_pk_mul_f32 v[98:99], v[102:103], v[94:95] op_sel_hi:[1,0]
	v_pk_mul_f32 v[100:101], v[112:113], v[94:95] op_sel_hi:[1,0]
	v_pk_mul_f32 v[102:103], v[114:115], v[94:95] op_sel_hi:[1,0]
	v_pk_mul_f32 v[108:109], v[126:127], v[94:95] op_sel_hi:[1,0]
	v_pk_mul_f32 v[112:113], v[128:129], v[94:95] op_sel_hi:[1,0]
	v_pk_mul_f32 v[114:115], v[144:145], v[94:95] op_sel_hi:[1,0]
	v_pk_fma_f32 v[30:31], v[38:39], v[90:91], v[30:31]
	v_pk_fma_f32 v[28:29], v[36:37], v[88:89], v[28:29]
	v_pk_fma_f32 v[10:11], v[54:55], v[118:119], v[10:11]
	v_pk_fma_f32 v[8:9], v[52:53], v[116:117], v[8:9]
	v_pk_fma_f32 v[26:27], v[34:35], v[98:99], v[26:27]
	v_pk_fma_f32 v[24:25], v[32:33], v[96:97], v[24:25]
	v_pk_fma_f32 v[22:23], v[46:47], v[102:103], v[22:23]
	v_pk_fma_f32 v[20:21], v[44:45], v[100:101], v[20:21]
	v_pk_fma_f32 v[18:19], v[42:43], v[108:109], v[18:19]
	v_pk_fma_f32 v[16:17], v[40:41], v[106:107], v[16:17]
	v_pk_fma_f32 v[14:15], v[58:59], v[114:115], v[14:15]
	v_pk_fma_f32 v[12:13], v[56:57], v[112:113], v[12:13]
	global_store_dwordx4 v[70:71], v[28:31], off offset:-4096 nt
	global_store_dwordx4 v[70:71], v[24:27], off offset:-3072 nt
	global_store_dwordx4 v[70:71], v[20:23], off offset:-2048 nt
	global_store_dwordx4 v[70:71], v[16:19], off offset:-1024 nt
	global_store_dwordx4 v[70:71], v[12:15], off nt
	global_store_dwordx4 v[70:71], v[8:11], off offset:1024 nt
	s_nop 1
	v_pk_mul_f32 v[8:9], v[122:123], v[94:95] op_sel_hi:[1,0]
	v_pk_mul_f32 v[10:11], v[104:105], v[94:95] op_sel_hi:[1,0]
	s_waitcnt vmcnt(7)
	v_pk_fma_f32 v[4:5], v[60:61], v[8:9], v[4:5]
	v_pk_fma_f32 v[6:7], v[62:63], v[10:11], v[6:7]
	global_store_dwordx4 v[70:71], v[4:7], off offset:2048 nt
	s_nop 1
	v_pk_mul_f32 v[4:5], v[110:111], v[94:95] op_sel_hi:[1,0]
	v_pk_mul_f32 v[6:7], v[92:93], v[94:95] op_sel_hi:[1,0]
	s_waitcnt vmcnt(7)
	v_pk_fma_f32 v[0:1], v[48:49], v[4:5], v[0:1]
	v_pk_fma_f32 v[2:3], v[50:51], v[6:7], v[2:3]
	global_store_dwordx4 v[70:71], v[0:3], off offset:3072 nt
	s_waitcnt vmcnt(8)
	v_readfirstlane_b32 s83, v237
	s_lshl_b32 s83, s83, 1
	s_add_u32 s83, s83, s86
	s_add_u32 s83, s83, s94
	s_lshl_b32 s83, s83, 3
	s_sub_u32 s84, s83, s82
	s_mov_b32 s82, s83
	s_mov_b32 s85, 0
	s_mov_b32 s0, s84
	s_lshl_b64 s[2:3], s[84:85], 12
	s_lshl_b64 s[4:5], s[84:85], 13
	v_add_u32_e32 v64, s0, v64
	v_cmp_lt_i32_e32 vcc, s15, v64
	v_lshl_add_u64 v[68:69], v[68:69], 0, s[2:3]
	s_or_b64 s[6:7], vcc, s[6:7]
	v_lshl_add_u64 v[70:71], v[70:71], 0, s[4:5]
	s_andn2_b64 exec, exec, s[6:7]
	s_cbranch_execnz .LBB0_1830
